# v11 + all five GEMM phases stage operand tiles row-major (128-B rows, XOR chunk swizzle): each LDS-DMA fetches 8 whole lines
# speedup vs baseline: 1.0041x; 1.0041x over previous
;     __host__ __device__ bool next(int i, Unit& u) const {
;         long L = (long)i * G + c; if (L >= (long)nwg * rep) return false; L %= nwg;
;         int wgid = (int)L; { const int q = nwg / NXCD, r = nwg % NXCD, xcd = wgid % NXCD, off = wgid / NXCD; wgid = (xcd < r ? xcd * (q + 1) : r * (q + 1) + (xcd - r) * q) + off; }
;         const int nig = WGM * nN, gid = wgid / nig, fm = gid * WGM, gsz = (nM - fm) < WGM ? (nM - fm) : WGM;
; template <class Epi, class Sched, bool ALIGN_EPI = false, bool SP2 = false>
; __device__ __forceinline__ void gemm_phase(PG8_LAS unsigned char* lds, const Gemm g, const Sched& S, const Epi& E) {
;     ...
;     for (int i = 0; i < 2; ++i) { int R, C; stage_rc(tid * 16 + i * 8192, R, C); const int Rb = Epi::PERM ? ((R & ~31) + perm32(R & 31)) : R;
;         voffA[i] = (unsigned)(R * K + C) * 2u; voffB[i] = (unsigned)(Rb * K + C) * 2u; }
;     const size_t kstep = (size_t)(BK * 2);
;     const size_t hstep = (size_t)HALF * K * 2;
;     const size_t tstep = 2 * hstep;
;     const unsigned ldsw = (unsigned)wid * 1024u;
;     const int aoff = lds_byte(wr * 64 + fr, fq * 8), boff = lds_byte(wc * 32 + fr, fq * 8);
;     ...
;     Unit cur, nxt; int ui = 0;
;     if (!S.next(0, cur)) return;
;     f32x4 acc[2][2][4][2];
; #pragma unroll
;     for (int a = 0; a < 2; ++a)
; #pragma unroll
;         for (int b = 0; b < 2; ++b)
; #pragma unroll
;             for (int m = 0; m < 4; ++m)
; #pragma unroll
;                 for (int n = 0; n < 2; ++n) acc[a][b][m][n] = (f32x4){0.f, 0.f, 0.f, 0.f};
;     bf16x8 At[4][2], B0[2][2], B1[2][2];
;     const char* cA = (const char*)(cur.seg ? g.A1 : g.A0) + (size_t)cur.pm * tstep; const char* cB = (const char*)(cur.seg ? g.B1 : g.B0) + (size_t)cur.pn * tstep;
;     S.a_ready(cur);
;     if constexpr (SP2) {
;         PG8_STAGE(PG8_SB(0, 0), cB, voffB); PG8_STAGE(PG8_SB(0, 1), cB + hstep, voffB); PG8_STAGE(PG8_SA(0, 0), cA, voffA); PG8_STAGE(PG8_SA(0, 1), cA + hstep, voffA);
;         if (wr == 1) PG8_BAR;
;         PG8_WAIT_V(2); PG8_BAR;
;         PG8_STAGE(PG8_SB(1, 0), cB + kstep, voffB); PG8_STAGE(PG8_SA(1, 0), cA + kstep, voffA); PG8_STAGE(PG8_SB(1, 1), cB + hstep + kstep, voffB);
;         PG8_WAIT_V(6); PG8_BAR;
;     } else {
;         PG8_STAGE(PG8_SB(0, 0), cB, voffB); PG8_STAGE(PG8_SA(0, 0), cA, voffA); PG8_STAGE(PG8_SB(0, 1), cB + hstep, voffB); PG8_STAGE(PG8_SA(0, 1), cA + hstep, voffA);
.LBB0_333:
	s_cmp_lt_i32 s28, 2
	s_cselect_b64 s[0:1], -1, 0
	s_add_u32 s10, s58, 0x2800000
	s_addc_u32 s11, s59, 0
	s_add_u32 s12, s58, 0x6800000
	s_addc_u32 s13, s59, 0
	s_add_u32 s16, s58, 0x8800000
	s_addc_u32 s17, s59, 0
	s_add_u32 s85, s58, 0xa800000
	s_addc_u32 s86, s59, 0
	s_add_u32 s89, s58, 0xc800000
	s_addc_u32 s90, s59, 0
	s_add_u32 s87, s58, 0xe800000
	s_addc_u32 s88, s59, 0
	s_add_u32 s14, s58, 0x10800000
	s_addc_u32 s15, s59, 0
	s_and_b64 s[0:1], s[0:1], s[42:43]
	s_andn2_b64 vcc, exec, s[0:1]
	s_cbranch_vccnz .LBB0_362
	s_cmpk_gt_i32 s2, 0x9ff
	v_readfirstlane_b32 s3, v164
	s_cbranch_scc1 .LBB0_362
	v_lshrrev_b32_e32 v0, 5, v164
	v_lshrrev_b32_e32 v2, 1, v164
	v_and_b32_e32 v0, 4, v0
	v_bfe_u32 v1, v164, 2, 2
	v_and_b32_e32 v144, 24, v2
	v_or3_b32 v0, v0, v1, v144
	v_lshlrev_b32_e32 v1, 4, v164
	v_writelane_b32 v255, s0, 0
	v_add_u32_e32 v8, 0x2000, v1
	v_lshrrev_b32_e32 v2, 7, v8
	v_writelane_b32 v255, s1, 1
	s_movk_i32 s0, 0xe0
	v_and_b32_e32 v4, 32, v164
	v_and_or_b32 v3, v2, s0, v0
	v_bitop3_b32 v9, v1, v4, 48 bitop3:0x6c
	v_and_b32_e32 v10, 64, v164
	v_bfe_u32 v11, v164, 2, 4
	s_movk_i32 s0, 0xf0
	v_or_b32_e32 v1, v9, v10
	v_and_or_b32 v2, v2, s0, v11
	v_and_b32_e32 v240, 7, v164
	v_bfe_u32 v241, v164, 4, 3
	v_xor_b32_e32 v240, v240, v241
	v_lshlrev_b32_e32 v240, 4, v240
	v_lshrrev_b32_e32 v241, 3, v164
	v_lshl_or_b32 v242, v241, 11, v240
	v_add_u32_e32 v243, 0x20000, v242
	v_bfe_u32 v244, v164, 5, 2
	v_lshlrev_b32_e32 v244, 3, v244
	v_bfe_u32 v245, v164, 7, 1
	v_lshl_or_b32 v244, v245, 2, v244
	v_bfe_u32 v245, v164, 3, 2
	v_or_b32_e32 v244, v244, v245
	v_bfe_u32 v245, v164, 8, 1
	v_lshl_or_b32 v247, v245, 5, v244
	v_lshl_or_b32 v244, v247, 11, v240
	v_add_u32_e32 v245, 0x20000, v244
	v_and_b32_e32 v246, 15, v164
	v_bfe_u32 v247, v164, 4, 2
	v_bfe_u32 v248, v164, 1, 3
	v_xor_b32_e32 v247, v247, v248
	v_lshlrev_b32_e32 v247, 4, v247
	v_lshl_or_b32 v246, v246, 7, v247
	v_mov_b32_e32 v148, v243
	v_lshrrev_b32_e32 v2, 3, v164
	s_movk_i32 s0, 0x60
	v_and_or_b32 v0, v2, s0, v0
	s_movk_i32 s0, 0x70
	v_mov_b32_e32 v150, v244
	v_and_or_b32 v0, v2, s0, v11
	s_mul_hi_i32 s0, s2, 0x66666667
	s_lshr_b32 s1, s0, 31
	s_ashr_i32 s0, s0, 10
	s_add_i32 s0, s0, s1
	s_mulk_i32 s0, 0xa00
	s_sub_i32 s0, s2, s0
	s_sext_i32_i16 s1, s0
	s_bfe_u32 s1, s1, 0x3001c
	s_add_i32 s1, s0, s1
	s_sext_i32_i16 s4, s1
	s_and_b32 s1, s1, 0xfff8
	s_lshr_b32 s6, s3, 6
	s_sub_i32 s0, s0, s1
	s_lshr_b32 s5, s3, 8
	s_lshl_b32 s51, s6, 10
	s_ashr_i32 s4, s4, 3
	s_sext_i32_i16 s1, s0
	s_cmp_lt_i32 s1, 0
	s_movk_i32 s1, 0x141
	s_cselect_b32 s1, s1, 0x140
	s_mul_i32 s0, s0, s1
	s_add_i32 s0, s0, s4
	s_sext_i32_i16 s1, s0
	s_mulk_i32 s1, 0x6667
	s_lshr_b32 s4, s1, 31
	s_ashr_i32 s1, s1, 22
	s_add_i32 s1, s1, s4
	s_lshl_b32 s7, s1, 3
	s_mulk_i32 s1, 0xa0
	s_sub_i32 s0, s0, s1
	s_sext_i32_i16 s1, s0
	v_writelane_b32 v255, s76, 2
	s_bfe_u32 s1, s1, 0x3001c
	v_writelane_b32 v255, s48, 3
	s_add_i32 s1, s0, s1
	s_sext_i32_i16 s4, s1
	v_writelane_b32 v255, s49, 4
	s_and_b32 s1, s1, 0xfff8
	v_writelane_b32 v255, s96, 5
	s_sub_i32 s0, s0, s1
	s_sext_i32_i16 s0, s0
	v_writelane_b32 v255, s97, 6
	v_writelane_b32 v255, s91, 7
	s_lshr_b32 s4, s4, 3
	s_add_i32 s42, s7, s0
	v_writelane_b32 v255, s94, 8
	s_ashr_i32 s43, s42, 31
	s_bfe_i64 s[30:31], s[4:5], 0x100000
	v_writelane_b32 v255, s95, 9
	s_lshl_b64 s[8:9], s[42:43], 19
	s_lshl_b64 s[30:31], s[30:31], 19
	v_writelane_b32 v255, s92, 10
	s_add_u32 s80, s72, s30
	s_addc_u32 s81, s73, s31
	v_writelane_b32 v255, s93, 11
	s_add_i32 s92, s51, 0
	s_add_i32 m0, s92, 0x10000
	v_mov_b32_e32 v146, v245
	global_load_lds_dwordx4 v150, s[80:81]
	s_add_i32 m0, s92, 0x12000
	s_add_u32 s30, s80, 0x40000
	global_load_lds_dwordx4 v146, s[80:81]
	s_addc_u32 s31, s81, 0
	s_add_i32 m0, s92, 0x14000
	v_mov_b32_e32 v152, v242
	global_load_lds_dwordx4 v150, s[30:31]
	s_add_i32 m0, s92, 0x16000
	s_add_u32 s78, s10, s8
	s_addc_u32 s79, s11, s9
	s_add_i32 s93, s92, 0x2000
	global_load_lds_dwordx4 v146, s[30:31]
	s_mov_b32 m0, s92
	s_add_u32 s8, s78, 0x40000
	global_load_lds_dwordx4 v152, s[78:79]
	s_mov_b32 m0, s93
	s_addc_u32 s9, s79, 0
	s_add_i32 s94, s92, 0x4000
	global_load_lds_dwordx4 v148, s[78:79]
	s_mov_b32 m0, s94
	s_add_i32 s95, s92, 0x6000
	global_load_lds_dwordx4 v152, s[8:9]
	s_mov_b32 m0, s95
	v_mov_b32_e32 v155, 0
	global_load_lds_dwordx4 v148, s[8:9]
	v_mov_b32_e32 v151, v155
	v_mov_b32_e32 v147, v155
	v_mov_b32_e32 v153, v155
	v_mov_b32_e32 v149, v155
	s_cmp_eq_u32 s5, 1
	s_mov_b32 s43, 0
	v_lshl_add_u64 v[6:7], s[80:81], 0, v[150:151]
	v_lshl_add_u64 v[4:5], s[80:81], 0, v[146:147]
	v_lshl_add_u64 v[0:1], s[78:79], 0, v[152:153]
	s_cselect_b64 s[44:45], -1, 0
	s_cmp_lg_u32 s5, 1
	v_lshl_add_u64 v[2:3], s[78:79], 0, v[148:149]
	s_cbranch_scc1 .LBB0_337
	s_barrier
; #define PG8_STAGE(bufoff, gbase, voff) do { _Pragma("unroll") for (int _i = 0; _i < 2; ++_i) \
;         __builtin_amdgcn_global_load_lds((const unsigned*)((const char*)(gbase) + (voff)[_i]), (PG8_LAS unsigned*)(lds + (bufoff) + ldsw + _i * 8192), 16, 0, 0); } while (0)
; #define PG8_WAIT_V(n) asm volatile("s_waitcnt vmcnt(" #n ")" ::: "memory")
; #define PG8_BAR __builtin_amdgcn_s_barrier()
; template <class Epi, class Sched, bool ALIGN_EPI = false, bool SP2 = false>
; __device__ __forceinline__ void gemm_phase(PG8_LAS unsigned char* lds, const Gemm g, const Sched& S, const Epi& E) {
;     ...
;     for (int i = 0; i < 2; ++i) { int R, C; stage_rc(tid * 16 + i * 8192, R, C); const int Rb = Epi::PERM ? ((R & ~31) + perm32(R & 31)) : R;
;         voffA[i] = (unsigned)(R * K + C) * 2u; voffB[i] = (unsigned)(Rb * K + C) * 2u; }
;     const size_t kstep = (size_t)(BK * 2);
;     const size_t hstep = (size_t)HALF * K * 2;
;     const size_t tstep = 2 * hstep;
;     const unsigned ldsw = (unsigned)wid * 1024u;
;     const int aoff = lds_byte(wr * 64 + fr, fq * 8), boff = lds_byte(wc * 32 + fr, fq * 8);
;     ...
;         PG8_STAGE(PG8_SB(0, 0), cB, voffB); PG8_STAGE(PG8_SB(0, 1), cB + hstep, voffB); PG8_STAGE(PG8_SA(0, 0), cA, voffA); PG8_STAGE(PG8_SA(0, 1), cA + hstep, voffA);
;         if (wr == 1) PG8_BAR;
;         PG8_WAIT_V(2); PG8_BAR;
;         PG8_STAGE(PG8_SB(1, 0), cB + kstep, voffB); PG8_STAGE(PG8_SA(1, 0), cA + kstep, voffA); PG8_STAGE(PG8_SB(1, 1), cB + hstep + kstep, voffB);
;         PG8_WAIT_V(6); PG8_BAR;
.LBB0_337:
	s_mov_b64 s[46:47], 0x80
	s_and_b32 s0, s6, 3
	s_add_i32 m0, s92, 0x18000
	v_lshl_add_u64 v[6:7], v[6:7], 0, s[46:47]
	s_lshl_b32 s1, s5, 13
	s_lshl_b32 s8, s0, 12
	s_ashr_i32 s96, s2, 31
	s_waitcnt vmcnt(2)
	s_barrier
	global_load_lds_dwordx4 v[6:7], off
	v_lshl_add_u64 v[4:5], v[4:5], 0, s[46:47]
	s_add_i32 m0, s92, 0x1a000
	s_add_i32 s97, s92, 0x8000
	s_add_i32 s34, s92, 0xa000
	global_load_lds_dwordx4 v[4:5], off
	v_lshl_add_u64 v[0:1], v[0:1], 0, s[46:47]
	s_mov_b32 m0, s97
	s_add_u32 s6, s80, 0x40080
	global_load_lds_dwordx4 v[0:1], off
	v_lshl_add_u64 v[0:1], v[2:3], 0, s[46:47]
	s_mov_b32 m0, s34
	s_addc_u32 s7, s81, 0
	global_load_lds_dwordx4 v[0:1], off
	s_add_i32 m0, s92, 0x1c000
	v_lshl_add_u64 v[0:1], s[6:7], 0, v[150:151]
	global_load_lds_dwordx4 v[0:1], off
	v_lshl_add_u64 v[0:1], s[6:7], 0, v[146:147]
	s_add_i32 m0, s92, 0x1e000
	v_lshlrev_b32_e32 v2, 2, v164
	global_load_lds_dwordx4 v[0:1], off
	v_and_b32_e32 v0, 15, v164
	v_lshlrev_b32_e32 v1, 1, v144
	v_lshl_or_b32 v145, s5, 6, v0
	v_lshl_or_b32 v0, v0, 6, v1
	v_and_b32_e32 v2, 32, v2
	v_or_b32_e32 v3, s1, v246
	v_lshlrev_b32_e32 v0, 6, v164
	s_movk_i32 s1, 0x3c0
	v_and_or_b32 v0, v0, s1, v1
	v_lshlrev_b32_e32 v154, 2, v144
	s_sext_i32_i16 s6, s4
	v_or_b32_e32 v157, s8, v246
	v_lshl_add_u64 v[0:1], s[58:59], 0, v[154:155]
	s_mov_b64 s[4:5], 0x100000
	v_lshl_add_u64 v[158:159], v[0:1], 0, s[4:5]
	v_lshlrev_b32_e32 v0, 8, v164
	v_and_b32_e32 v0, 0x38000, v0
	v_lshlrev_b32_e32 v1, 11, v11
	v_or3_b32 v0, v9, v0, v1
	v_mov_b32_e32 v162, v242
	v_lshlrev_b32_e32 v0, 4, v8
	s_cmpk_lt_u32 s3, 0x100
	v_and_b32_e32 v0, 0x78000, v0
	s_waitcnt vmcnt(6)
	s_cselect_b64 s[48:49], -1, 0
	v_lshl_or_b32 v156, s0, 5, v144
	s_lshl_b32 s0, s0, 6
	v_or3_b32 v0, v9, v0, v1
	v_lshlrev_b32_e32 v154, 1, v156
	v_mov_b32_e32 v166, v243
	s_add_i32 s8, 0, 0x10000
	s_add_i32 s9, 0, 0x14000
	s_lshl_b32 s0, s0, 1
	v_mbcnt_lo_u32_b32 v0, -1, 0
	v_or_b32_e32 v184, 0xfffffa00, v156
	s_ashr_i32 s35, s33, 31
	v_lshl_add_u64 v[160:161], s[16:17], 0, v[154:155]
	v_mov_b32_e32 v163, v155
	v_mov_b32_e32 v167, v155
	v_mov_b64_e32 v[168:169], 0xa00
	v_mov_b64_e32 v[170:171], 0x9ff
	v_add_u32_e32 v185, s8, v157
	v_xor_b32_e32 v249, 64, v185
	v_add_u32_e32 v186, s9, v157
	v_xor_b32_e32 v250, 64, v186
	v_add_u32_e32 v187, 0, v3
	v_xor_b32_e32 v251, 64, v187
	s_mov_b32 s50, 0xbfb8aa3b
	v_writelane_b32 v255, s0, 12
	v_mov_b32_e32 v188, 0x358637bd
	v_mov_b32_e32 v189, 0x3e38aa3b
	v_mbcnt_hi_u32_b32 v190, -1, v0
	s_mov_b32 s7, 0
	s_barrier
	s_branch .LBB0_340

; #define PG8_STAGE(bufoff, gbase, voff) do { _Pragma("unroll") for (int _i = 0; _i < 2; ++_i) \
;         __builtin_amdgcn_global_load_lds((const unsigned*)((const char*)(gbase) + (voff)[_i]), (PG8_LAS unsigned*)(lds + (bufoff) + ldsw + _i * 8192), 16, 0, 0); } while (0)
; #define PG8_LDA(dst, b, h) do { _Pragma("unroll") for (int m = 0; m < 4; ++m) _Pragma("unroll") for (int k = 0; k < 2; ++k) dst[m][k] = *(const PG8_LAS bf16x8*)(lds + PG8_SA(b, h) + aoff + m * 2048 + k * 1024); } while (0)
; #define PG8_LDB(dst, b, h) do { _Pragma("unroll") for (int n = 0; n < 2; ++n) _Pragma("unroll") for (int k = 0; k < 2; ++k) dst[n][k] = *(const PG8_LAS bf16x8*)(lds + PG8_SB(b, h) + boff + n * 2048 + k * 1024); } while (0)
; #define PG8_MMA(ai, bj, At, Bt) do { __builtin_amdgcn_s_setprio(1); _Pragma("unroll") for (int m = 0; m < 4; ++m) _Pragma("unroll") for (int n = 0; n < 2; ++n) _Pragma("unroll") for (int k = 0; k < 2; ++k) \
;         acc[ai][bj][m][n] = __builtin_amdgcn_mfma_f32_16x16x32_bf16(Bt[n][k], At[m][k], acc[ai][bj][m][n], 0, 0, 0); __builtin_amdgcn_s_setprio(0); } while (0)
; #define PG8_WAIT_V(n) asm volatile("s_waitcnt vmcnt(" #n ")" ::: "memory")
; #define PG8_WAIT_L(n) asm volatile("s_waitcnt lgkmcnt(" #n ")" ::: "memory")
; #define PG8_BAR __builtin_amdgcn_s_barrier()
; #define PG8_SCHED __builtin_amdgcn_sched_barrier(0)
; template <class Epi, class Sched, bool ALIGN_EPI = false, bool SP2 = false>
; __device__ __forceinline__ void gemm_phase(PG8_LAS unsigned char* lds, const Gemm g, const Sched& S, const Epi& E) {
;     ...
;             PG8_LDB(B0, 0, 0); PG8_LDB(B1, 0, 1); PG8_SCHED; PG8_LDA(At, 0, 0); PG8_STAGE(PG8_SA(1, 1), a1 + hstep, voffA);
;             PG8_WAIT_V(8); PG8_WAIT_L(0); PG8_BAR; PG8_MMA(0, 0, At, B0); PG8_MMA(0, 1, At, B1); PG8_BAR; PG8_SCHED;
;             PG8_LDA(At, 0, 1); PG8_STAGE(PG8_SB(0, 0), b2, voffB); PG8_STAGE(PG8_SB(0, 1), b2 + hstep, voffB); PG8_STAGE(PG8_SA(0, 0), a2, voffA);
;             PG8_WAIT_V(8); PG8_WAIT_L(0); PG8_BAR; PG8_MMA(1, 0, At, B0); PG8_MMA(1, 1, At, B1); PG8_BAR; PG8_SCHED;
.LBB0_343:
	ds_read_b128 v[128:131], v185
	ds_read_b128 v[132:135], v249
	ds_read_b128 v[136:139], v185 offset:2048
	ds_read_b128 v[140:143], v249 offset:2048
	ds_read_b128 v[172:175], v186
	ds_read_b128 v[176:179], v250
	ds_read_b128 v[180:183], v186 offset:2048
	ds_read_b128 v[192:195], v250 offset:2048
	s_add_u32 s0, s78, 0xfffc0080
	s_addc_u32 s1, s79, -1
	s_cmp_eq_u32 s30, 12
	s_cselect_b32 s83, s53, s1
	s_cselect_b32 s82, vcc_lo, s0
	s_cselect_b32 s81, s55, s3
	s_cselect_b32 s80, vcc_hi, s84
	s_add_i32 m0, s92, 0xc000
	ds_read_b128 v[196:199], v187
	ds_read_b128 v[200:203], v251
	ds_read_b128 v[204:207], v187 offset:2048
	ds_read_b128 v[208:211], v251 offset:2048
	ds_read_b128 v[212:215], v187 offset:4096
	ds_read_b128 v[216:219], v251 offset:4096
	ds_read_b128 v[220:223], v187 offset:6144
	ds_read_b128 v[224:227], v251 offset:6144
	global_load_lds_dwordx4 v162, s[78:79]
	s_add_i32 m0, s92, 0xe000
	s_nop 0
	global_load_lds_dwordx4 v166, s[78:79]
	s_waitcnt vmcnt(8)
	s_waitcnt lgkmcnt(0)
	s_barrier
	s_setprio 1
	s_waitcnt lgkmcnt(0)
	v_mfma_f32_16x16x32_bf16 v[124:127], v[128:131], v[196:199], v[124:127]
	v_mfma_f32_16x16x32_bf16 v[120:123], v[136:139], v[196:199], v[120:123]
	v_mfma_f32_16x16x32_bf16 v[116:119], v[128:131], v[204:207], v[116:119]
	v_mfma_f32_16x16x32_bf16 v[112:115], v[136:139], v[204:207], v[112:115]
	v_mfma_f32_16x16x32_bf16 v[100:103], v[128:131], v[212:215], v[100:103]
	v_mfma_f32_16x16x32_bf16 v[96:99], v[136:139], v[212:215], v[96:99]
	v_mfma_f32_16x16x32_bf16 v[84:87], v[128:131], v[220:223], v[84:87]
	v_mfma_f32_16x16x32_bf16 v[80:83], v[136:139], v[220:223], v[80:83]
	v_mfma_f32_16x16x32_bf16 v[124:127], v[132:135], v[200:203], v[124:127]
	v_mfma_f32_16x16x32_bf16 v[120:123], v[140:143], v[200:203], v[120:123]
	v_mfma_f32_16x16x32_bf16 v[116:119], v[132:135], v[208:211], v[116:119]
	v_mfma_f32_16x16x32_bf16 v[112:115], v[140:143], v[208:211], v[112:115]
	v_mfma_f32_16x16x32_bf16 v[100:103], v[132:135], v[216:219], v[100:103]
	v_mfma_f32_16x16x32_bf16 v[96:99], v[140:143], v[216:219], v[96:99]
	v_mfma_f32_16x16x32_bf16 v[84:87], v[132:135], v[224:227], v[84:87]
	v_mfma_f32_16x16x32_bf16 v[80:83], v[140:143], v[224:227], v[80:83]
	s_setprio 0
	s_setprio 1
	v_mfma_f32_16x16x32_bf16 v[108:111], v[172:175], v[196:199], v[108:111]
	v_mfma_f32_16x16x32_bf16 v[104:107], v[180:183], v[196:199], v[104:107]
	v_mfma_f32_16x16x32_bf16 v[92:95], v[172:175], v[204:207], v[92:95]
	v_mfma_f32_16x16x32_bf16 v[88:91], v[180:183], v[204:207], v[88:91]
	v_mfma_f32_16x16x32_bf16 v[76:79], v[172:175], v[212:215], v[76:79]
	v_mfma_f32_16x16x32_bf16 v[72:75], v[180:183], v[212:215], v[72:75]
	v_mfma_f32_16x16x32_bf16 v[68:71], v[172:175], v[220:223], v[68:71]
	v_mfma_f32_16x16x32_bf16 v[64:67], v[180:183], v[220:223], v[64:67]
	v_mfma_f32_16x16x32_bf16 v[108:111], v[176:179], v[200:203], v[108:111]
	v_mfma_f32_16x16x32_bf16 v[104:107], v[192:195], v[200:203], v[104:107]
	v_mfma_f32_16x16x32_bf16 v[92:95], v[176:179], v[208:211], v[92:95]
	v_mfma_f32_16x16x32_bf16 v[88:91], v[192:195], v[208:211], v[88:91]
	v_mfma_f32_16x16x32_bf16 v[76:79], v[176:179], v[216:219], v[76:79]
	v_mfma_f32_16x16x32_bf16 v[72:75], v[192:195], v[216:219], v[72:75]
	v_mfma_f32_16x16x32_bf16 v[68:71], v[176:179], v[224:227], v[68:71]
	v_mfma_f32_16x16x32_bf16 v[64:67], v[192:195], v[224:227], v[64:67]
	s_setprio 0
	s_barrier
	s_add_i32 s0, s8, s51
	s_mov_b32 m0, s0
	ds_read_b128 v[196:199], v187 offset:16384
	ds_read_b128 v[200:203], v251 offset:16384
	ds_read_b128 v[204:207], v187 offset:18432
	ds_read_b128 v[208:211], v251 offset:18432
	ds_read_b128 v[212:215], v187 offset:20480
	ds_read_b128 v[216:219], v251 offset:20480
	ds_read_b128 v[220:223], v187 offset:22528
	ds_read_b128 v[224:227], v251 offset:22528
	global_load_lds_dwordx4 v150, s[80:81]
	s_add_i32 m0, s0, 0x2000
	s_add_u32 s0, s80, 0x40000
	s_addc_u32 s1, s81, 0
	s_add_i32 s31, s9, s51
	global_load_lds_dwordx4 v146, s[80:81]
	s_mov_b32 m0, s31
	s_nop 0
	global_load_lds_dwordx4 v150, s[0:1]
	s_add_i32 m0, s31, 0x2000
	s_nop 0
	global_load_lds_dwordx4 v146, s[0:1]
	s_mov_b32 m0, s92
	s_nop 0
	global_load_lds_dwordx4 v152, s[82:83]
	s_mov_b32 m0, s93
	s_nop 0
	global_load_lds_dwordx4 v148, s[82:83]
	s_waitcnt vmcnt(8)
	s_waitcnt lgkmcnt(0)
	s_barrier
	s_setprio 1
	s_waitcnt lgkmcnt(0)
	v_mfma_f32_16x16x32_bf16 v[60:63], v[128:131], v[196:199], v[60:63]
	v_mfma_f32_16x16x32_bf16 v[56:59], v[136:139], v[196:199], v[56:59]
	v_mfma_f32_16x16x32_bf16 v[52:55], v[128:131], v[204:207], v[52:55]
	v_mfma_f32_16x16x32_bf16 v[48:51], v[136:139], v[204:207], v[48:51]
	v_mfma_f32_16x16x32_bf16 v[36:39], v[128:131], v[212:215], v[36:39]
	v_mfma_f32_16x16x32_bf16 v[32:35], v[136:139], v[212:215], v[32:35]
	v_mfma_f32_16x16x32_bf16 v[20:23], v[128:131], v[220:223], v[20:23]
	v_mfma_f32_16x16x32_bf16 v[16:19], v[136:139], v[220:223], v[16:19]
	v_mfma_f32_16x16x32_bf16 v[60:63], v[132:135], v[200:203], v[60:63]
	v_mfma_f32_16x16x32_bf16 v[56:59], v[140:143], v[200:203], v[56:59]
	v_mfma_f32_16x16x32_bf16 v[52:55], v[132:135], v[208:211], v[52:55]
	v_mfma_f32_16x16x32_bf16 v[48:51], v[140:143], v[208:211], v[48:51]
	v_mfma_f32_16x16x32_bf16 v[36:39], v[132:135], v[216:219], v[36:39]
	v_mfma_f32_16x16x32_bf16 v[32:35], v[140:143], v[216:219], v[32:35]
	v_mfma_f32_16x16x32_bf16 v[20:23], v[132:135], v[224:227], v[20:23]
	v_mfma_f32_16x16x32_bf16 v[16:19], v[140:143], v[224:227], v[16:19]
	s_setprio 0
	s_setprio 1
	v_mfma_f32_16x16x32_bf16 v[44:47], v[172:175], v[196:199], v[44:47]
	v_mfma_f32_16x16x32_bf16 v[40:43], v[180:183], v[196:199], v[40:43]
	v_mfma_f32_16x16x32_bf16 v[28:31], v[172:175], v[204:207], v[28:31]
	v_mfma_f32_16x16x32_bf16 v[24:27], v[180:183], v[204:207], v[24:27]
	v_mfma_f32_16x16x32_bf16 v[12:15], v[172:175], v[212:215], v[12:15]
	v_mfma_f32_16x16x32_bf16 v[8:11], v[180:183], v[212:215], v[8:11]
	v_mfma_f32_16x16x32_bf16 v[4:7], v[172:175], v[220:223], v[4:7]
	v_mfma_f32_16x16x32_bf16 v[0:3], v[180:183], v[220:223], v[0:3]
	v_mfma_f32_16x16x32_bf16 v[44:47], v[176:179], v[200:203], v[44:47]
	v_mfma_f32_16x16x32_bf16 v[40:43], v[192:195], v[200:203], v[40:43]
	v_mfma_f32_16x16x32_bf16 v[28:31], v[176:179], v[208:211], v[28:31]
	v_mfma_f32_16x16x32_bf16 v[24:27], v[192:195], v[208:211], v[24:27]
	v_mfma_f32_16x16x32_bf16 v[12:15], v[176:179], v[216:219], v[12:15]
	v_mfma_f32_16x16x32_bf16 v[8:11], v[192:195], v[216:219], v[8:11]
	v_mfma_f32_16x16x32_bf16 v[4:7], v[176:179], v[224:227], v[4:7]
	v_mfma_f32_16x16x32_bf16 v[0:3], v[192:195], v[224:227], v[0:3]
	s_setprio 0
	s_barrier
; #define PG8_STAGE(bufoff, gbase, voff) do { _Pragma("unroll") for (int _i = 0; _i < 2; ++_i) \
;         __builtin_amdgcn_global_load_lds((const unsigned*)((const char*)(gbase) + (voff)[_i]), (PG8_LAS unsigned*)(lds + (bufoff) + ldsw + _i * 8192), 16, 0, 0); } while (0)
; #define PG8_LDA(dst, b, h) do { _Pragma("unroll") for (int m = 0; m < 4; ++m) _Pragma("unroll") for (int k = 0; k < 2; ++k) dst[m][k] = *(const PG8_LAS bf16x8*)(lds + PG8_SA(b, h) + aoff + m * 2048 + k * 1024); } while (0)
; #define PG8_LDB(dst, b, h) do { _Pragma("unroll") for (int n = 0; n < 2; ++n) _Pragma("unroll") for (int k = 0; k < 2; ++k) dst[n][k] = *(const PG8_LAS bf16x8*)(lds + PG8_SB(b, h) + boff + n * 2048 + k * 1024); } while (0)
; #define PG8_MMA(ai, bj, At, Bt) do { __builtin_amdgcn_s_setprio(1); _Pragma("unroll") for (int m = 0; m < 4; ++m) _Pragma("unroll") for (int n = 0; n < 2; ++n) _Pragma("unroll") for (int k = 0; k < 2; ++k) \
;         acc[ai][bj][m][n] = __builtin_amdgcn_mfma_f32_16x16x32_bf16(Bt[n][k], At[m][k], acc[ai][bj][m][n], 0, 0, 0); __builtin_amdgcn_s_setprio(0); } while (0)
; #define PG8_WAIT_V(n) asm volatile("s_waitcnt vmcnt(" #n ")" ::: "memory")
; #define PG8_WAIT_L(n) asm volatile("s_waitcnt lgkmcnt(" #n ")" ::: "memory")
; template <class Epi, class Sched, bool ALIGN_EPI = false, bool SP2 = false>
; __device__ __forceinline__ void gemm_phase(PG8_LAS unsigned char* lds, const Gemm g, const Sched& S, const Epi& E) {
;     ...
;         for (int t = 0; t < nt; t += 2) {
;             const bool last = (t == nt - 2);
;             const char* a1 = cA + (size_t)(t + 1) * kstep;
;             const char* a2 = last ? nA : cA + (size_t)(t + 2) * kstep; const char* b2 = last ? nB : cB + (size_t)(t + 2) * kstep;
;             const char* a3 = a2 + kstep; const char* b3 = b2 + kstep;
;             if (last && has_next) S.a_ready(nxt);
;     ...
;             PG8_LDB(B0, 1, 0); PG8_LDB(B1, 1, 1); PG8_SCHED; PG8_LDA(At, 1, 0); PG8_STAGE(PG8_SA(0, 1), a2 + hstep, voffA);
;             PG8_WAIT_V(8); PG8_WAIT_L(0); PG8_BAR; PG8_MMA(0, 0, At, B0); PG8_MMA(0, 1, At, B1); PG8_BAR; PG8_SCHED;
;             PG8_LDA(At, 1, 1); PG8_STAGE(PG8_SB(1, 0), b3, voffB); PG8_STAGE(PG8_SB(1, 1), b3 + hstep, voffB); PG8_STAGE(PG8_SA(1, 0), a3, voffA);
;             PG8_WAIT_V(8); PG8_WAIT_L(0); PG8_BAR; PG8_MMA(1, 0, At, B0); PG8_MMA(1, 1, At, B1); PG8_BAR; PG8_SCHED;
	s_add_i32 s31, 0, 0x18000
	s_add_i32 s91, 0, 0x1c000
	v_add_u32_e32 v140, s31, v157
	v_xor_b32_e32 v252, 64, v140
	v_add_u32_e32 v154, s91, v157
	v_xor_b32_e32 v253, 64, v154
	ds_read_b128 v[128:131], v140
	ds_read_b128 v[132:135], v252
	ds_read_b128 v[136:139], v140 offset:2048
	ds_read_b128 v[140:143], v252 offset:2048
	ds_read_b128 v[172:175], v154
	ds_read_b128 v[176:179], v253
	ds_read_b128 v[180:183], v154 offset:2048
	ds_read_b128 v[192:195], v253 offset:2048
	s_add_u32 s0, s82, 0x40000
	s_addc_u32 s1, s83, 0
	s_mov_b32 m0, s94
	ds_read_b128 v[196:199], v187 offset:32768
	ds_read_b128 v[200:203], v251 offset:32768
	ds_read_b128 v[204:207], v187 offset:34816
	ds_read_b128 v[208:211], v251 offset:34816
	ds_read_b128 v[212:215], v187 offset:36864
	ds_read_b128 v[216:219], v251 offset:36864
	ds_read_b128 v[220:223], v187 offset:38912
	ds_read_b128 v[224:227], v251 offset:38912
	global_load_lds_dwordx4 v152, s[0:1]
	s_mov_b32 m0, s95
	s_nop 0
	global_load_lds_dwordx4 v148, s[0:1]
	s_add_u32 s100, s80, 0x80
	s_addc_u32 s101, s81, 0
	s_add_u32 s98, s82, 0x80
	s_addc_u32 s99, s83, 0
	s_waitcnt vmcnt(8)
	s_waitcnt lgkmcnt(0)
	s_barrier
	s_setprio 1
	s_waitcnt lgkmcnt(0)
	v_mfma_f32_16x16x32_bf16 v[124:127], v[128:131], v[196:199], v[124:127]
	v_mfma_f32_16x16x32_bf16 v[120:123], v[136:139], v[196:199], v[120:123]
	v_mfma_f32_16x16x32_bf16 v[116:119], v[128:131], v[204:207], v[116:119]
	v_mfma_f32_16x16x32_bf16 v[112:115], v[136:139], v[204:207], v[112:115]
	v_mfma_f32_16x16x32_bf16 v[100:103], v[128:131], v[212:215], v[100:103]
	v_mfma_f32_16x16x32_bf16 v[96:99], v[136:139], v[212:215], v[96:99]
	v_mfma_f32_16x16x32_bf16 v[84:87], v[128:131], v[220:223], v[84:87]
	v_mfma_f32_16x16x32_bf16 v[80:83], v[136:139], v[220:223], v[80:83]
	v_mfma_f32_16x16x32_bf16 v[124:127], v[132:135], v[200:203], v[124:127]
	v_mfma_f32_16x16x32_bf16 v[120:123], v[140:143], v[200:203], v[120:123]
	v_mfma_f32_16x16x32_bf16 v[116:119], v[132:135], v[208:211], v[116:119]
	v_mfma_f32_16x16x32_bf16 v[112:115], v[140:143], v[208:211], v[112:115]
	v_mfma_f32_16x16x32_bf16 v[100:103], v[132:135], v[216:219], v[100:103]
	v_mfma_f32_16x16x32_bf16 v[96:99], v[140:143], v[216:219], v[96:99]
	v_mfma_f32_16x16x32_bf16 v[84:87], v[132:135], v[224:227], v[84:87]
	v_mfma_f32_16x16x32_bf16 v[80:83], v[140:143], v[224:227], v[80:83]
	s_setprio 0
	s_setprio 1
	v_mfma_f32_16x16x32_bf16 v[108:111], v[172:175], v[196:199], v[108:111]
	v_mfma_f32_16x16x32_bf16 v[104:107], v[180:183], v[196:199], v[104:107]
	v_mfma_f32_16x16x32_bf16 v[92:95], v[172:175], v[204:207], v[92:95]
	v_mfma_f32_16x16x32_bf16 v[88:91], v[180:183], v[204:207], v[88:91]
	v_mfma_f32_16x16x32_bf16 v[76:79], v[172:175], v[212:215], v[76:79]
	v_mfma_f32_16x16x32_bf16 v[72:75], v[180:183], v[212:215], v[72:75]
	v_mfma_f32_16x16x32_bf16 v[68:71], v[172:175], v[220:223], v[68:71]
	v_mfma_f32_16x16x32_bf16 v[64:67], v[180:183], v[220:223], v[64:67]
	v_mfma_f32_16x16x32_bf16 v[108:111], v[176:179], v[200:203], v[108:111]
	v_mfma_f32_16x16x32_bf16 v[104:107], v[192:195], v[200:203], v[104:107]
	v_mfma_f32_16x16x32_bf16 v[92:95], v[176:179], v[208:211], v[92:95]
	v_mfma_f32_16x16x32_bf16 v[88:91], v[192:195], v[208:211], v[88:91]
	v_mfma_f32_16x16x32_bf16 v[76:79], v[176:179], v[216:219], v[76:79]
	v_mfma_f32_16x16x32_bf16 v[72:75], v[192:195], v[216:219], v[72:75]
	v_mfma_f32_16x16x32_bf16 v[68:71], v[176:179], v[224:227], v[68:71]
	v_mfma_f32_16x16x32_bf16 v[64:67], v[192:195], v[224:227], v[64:67]
	s_setprio 0
	s_barrier
	s_add_i32 s0, s31, s51
	s_mov_b32 m0, s0
	ds_read_b128 v[196:199], v187 offset:49152
	ds_read_b128 v[200:203], v251 offset:49152
	ds_read_b128 v[204:207], v187 offset:51200
	ds_read_b128 v[208:211], v251 offset:51200
	ds_read_b128 v[212:215], v187 offset:53248
	ds_read_b128 v[216:219], v251 offset:53248
	ds_read_b128 v[220:223], v187 offset:55296
	ds_read_b128 v[224:227], v251 offset:55296
	global_load_lds_dwordx4 v150, s[100:101]
	s_add_i32 m0, s0, 0x2000
	s_add_u32 s0, s80, 0x40080
	s_addc_u32 s1, s81, 0
	s_add_i32 s31, s91, s51
	global_load_lds_dwordx4 v146, s[100:101]
	s_mov_b32 m0, s31
	s_nop 0
	global_load_lds_dwordx4 v150, s[0:1]
	s_add_i32 m0, s31, 0x2000
	s_nop 0
	global_load_lds_dwordx4 v146, s[0:1]
	s_mov_b32 m0, s97
	s_nop 0
	global_load_lds_dwordx4 v152, s[98:99]
	s_mov_b32 m0, s34
	s_nop 0
	global_load_lds_dwordx4 v148, s[98:99]
	s_waitcnt vmcnt(8)
	s_waitcnt lgkmcnt(0)
	s_barrier
	s_setprio 1
	s_waitcnt lgkmcnt(0)
	v_mfma_f32_16x16x32_bf16 v[60:63], v[128:131], v[196:199], v[60:63]
	v_mfma_f32_16x16x32_bf16 v[56:59], v[136:139], v[196:199], v[56:59]
	v_mfma_f32_16x16x32_bf16 v[52:55], v[128:131], v[204:207], v[52:55]
	v_mfma_f32_16x16x32_bf16 v[48:51], v[136:139], v[204:207], v[48:51]
	v_mfma_f32_16x16x32_bf16 v[36:39], v[128:131], v[212:215], v[36:39]
	v_mfma_f32_16x16x32_bf16 v[32:35], v[136:139], v[212:215], v[32:35]
	v_mfma_f32_16x16x32_bf16 v[20:23], v[128:131], v[220:223], v[20:23]
	v_mfma_f32_16x16x32_bf16 v[16:19], v[136:139], v[220:223], v[16:19]
	v_mfma_f32_16x16x32_bf16 v[60:63], v[132:135], v[200:203], v[60:63]
	v_mfma_f32_16x16x32_bf16 v[56:59], v[140:143], v[200:203], v[56:59]
	v_mfma_f32_16x16x32_bf16 v[52:55], v[132:135], v[208:211], v[52:55]
	v_mfma_f32_16x16x32_bf16 v[48:51], v[140:143], v[208:211], v[48:51]
	v_mfma_f32_16x16x32_bf16 v[36:39], v[132:135], v[216:219], v[36:39]
	v_mfma_f32_16x16x32_bf16 v[32:35], v[140:143], v[216:219], v[32:35]
	v_mfma_f32_16x16x32_bf16 v[20:23], v[132:135], v[224:227], v[20:23]
	v_mfma_f32_16x16x32_bf16 v[16:19], v[140:143], v[224:227], v[16:19]
	s_setprio 0
	s_setprio 1
	v_mfma_f32_16x16x32_bf16 v[44:47], v[172:175], v[196:199], v[44:47]
	v_mfma_f32_16x16x32_bf16 v[40:43], v[180:183], v[196:199], v[40:43]
	v_mfma_f32_16x16x32_bf16 v[28:31], v[172:175], v[204:207], v[28:31]
	v_mfma_f32_16x16x32_bf16 v[24:27], v[180:183], v[204:207], v[24:27]
	v_mfma_f32_16x16x32_bf16 v[12:15], v[172:175], v[212:215], v[12:15]
	v_mfma_f32_16x16x32_bf16 v[8:11], v[180:183], v[212:215], v[8:11]
	v_mfma_f32_16x16x32_bf16 v[4:7], v[172:175], v[220:223], v[4:7]
	v_mfma_f32_16x16x32_bf16 v[0:3], v[180:183], v[220:223], v[0:3]
	v_mfma_f32_16x16x32_bf16 v[44:47], v[176:179], v[200:203], v[44:47]
	v_mfma_f32_16x16x32_bf16 v[40:43], v[192:195], v[200:203], v[40:43]
	v_mfma_f32_16x16x32_bf16 v[28:31], v[176:179], v[208:211], v[28:31]
	v_mfma_f32_16x16x32_bf16 v[24:27], v[192:195], v[208:211], v[24:27]
	v_mfma_f32_16x16x32_bf16 v[12:15], v[176:179], v[216:219], v[12:15]
	v_mfma_f32_16x16x32_bf16 v[8:11], v[192:195], v[216:219], v[8:11]
	v_mfma_f32_16x16x32_bf16 v[4:7], v[176:179], v[224:227], v[4:7]
	v_mfma_f32_16x16x32_bf16 v[0:3], v[192:195], v[224:227], v[0:3]
	s_setprio 0
	s_barrier
	s_add_i32 s30, s30, 2
	s_add_u32 s78, s78, 0x100
	s_addc_u32 s79, s79, 0
	s_add_u32 s84, s84, 0x100
	s_addc_u32 s3, s3, 0
	s_cmp_gt_u32 s30, 13
	s_cbranch_scc0 .LBB0_343
	s_and_b64 vcc, exec, s[48:49]
	s_cbranch_vccz .LBB0_346
	s_barrier

;     __host__ __device__ bool next(int i, Unit& u) const {
;         long L = (long)i * G + c; if (L >= (long)nwg * rep) return false; L %= nwg;
;         int wgid = (int)L; { const int q = nwg / NXCD, r = nwg % NXCD, xcd = wgid % NXCD, off = wgid / NXCD; wgid = (xcd < r ? xcd * (q + 1) : r * (q + 1) + (xcd - r) * q) + off; }
;         const int nig = WGM * nN, gid = wgid / nig, fm = gid * WGM, gsz = (nM - fm) < WGM ? (nM - fm) : WGM;
; template <class Epi, class Sched, bool ALIGN_EPI = false, bool SP2 = false>
; __device__ __forceinline__ void gemm_phase(PG8_LAS unsigned char* lds, const Gemm g, const Sched& S, const Epi& E) {
;     ...
;     for (int i = 0; i < 2; ++i) { int R, C; stage_rc(tid * 16 + i * 8192, R, C); const int Rb = Epi::PERM ? ((R & ~31) + perm32(R & 31)) : R;
;         voffA[i] = (unsigned)(R * K + C) * 2u; voffB[i] = (unsigned)(Rb * K + C) * 2u; }
;     const size_t kstep = (size_t)(BK * 2);
;     const size_t hstep = (size_t)HALF * K * 2;
;     const size_t tstep = 2 * hstep;
;     const unsigned ldsw = (unsigned)wid * 1024u;
;     const int aoff = lds_byte(wr * 64 + fr, fq * 8), boff = lds_byte(wc * 32 + fr, fq * 8);
;     ...
;     Unit cur, nxt; int ui = 0;
;     if (!S.next(0, cur)) return;
;     f32x4 acc[2][2][4][2];
; #pragma unroll
;     for (int a = 0; a < 2; ++a)
; #pragma unroll
;         for (int b = 0; b < 2; ++b)
; #pragma unroll
;             for (int m = 0; m < 4; ++m)
; #pragma unroll
;                 for (int n = 0; n < 2; ++n) acc[a][b][m][n] = (f32x4){0.f, 0.f, 0.f, 0.f};
;     bf16x8 At[4][2], B0[2][2], B1[2][2];
;     const char* cA = (const char*)(cur.seg ? g.A1 : g.A0) + (size_t)cur.pm * tstep; const char* cB = (const char*)(cur.seg ? g.B1 : g.B0) + (size_t)cur.pn * tstep;
;     S.a_ready(cur);
;     if constexpr (SP2) {
;         PG8_STAGE(PG8_SB(0, 0), cB, voffB); PG8_STAGE(PG8_SB(0, 1), cB + hstep, voffB); PG8_STAGE(PG8_SA(0, 0), cA, voffA); PG8_STAGE(PG8_SA(0, 1), cA + hstep, voffA);
;         if (wr == 1) PG8_BAR;
;         PG8_WAIT_V(2); PG8_BAR;
;         PG8_STAGE(PG8_SB(1, 0), cB + kstep, voffB); PG8_STAGE(PG8_SA(1, 0), cA + kstep, voffA); PG8_STAGE(PG8_SB(1, 1), cB + hstep + kstep, voffB);
;         PG8_WAIT_V(6); PG8_BAR;
;     } else {
;         PG8_STAGE(PG8_SB(0, 0), cB, voffB); PG8_STAGE(PG8_SA(0, 0), cA, voffA); PG8_STAGE(PG8_SB(0, 1), cB + hstep, voffB); PG8_STAGE(PG8_SA(0, 1), cA + hstep, voffA);
.LBB0_561:
	v_lshrrev_b32_e32 v3, 1, v164
	v_and_b32_e32 v12, 24, v3
	v_lshrrev_b32_e32 v3, 5, v164
	v_and_b32_e32 v3, 4, v3
	v_bfe_u32 v4, v164, 2, 2
	v_lshlrev_b32_e32 v0, 4, v164
	v_and_b32_e32 v1, 32, v164
	v_bfe_u32 v11, v164, 2, 4
	v_or3_b32 v3, v3, v4, v12
	v_lshrrev_b32_e32 v4, 3, v164
	s_movk_i32 s7, 0x70
	v_bitop3_b32 v1, v0, v1, 48 bitop3:0x6c
	v_and_b32_e32 v10, 64, v164
	v_and_or_b32 v5, v4, s7, v11
	s_movk_i32 s7, 0x60
	v_add_u32_e32 v13, 0x2000, v0
	v_or_b32_e32 v2, v1, v10
	v_and_or_b32 v4, v4, s7, v3
	v_lshrrev_b32_e32 v0, 7, v13
	s_movk_i32 s7, 0xf0
	v_and_b32_e32 v240, 7, v164
	v_bfe_u32 v241, v164, 4, 3
	v_xor_b32_e32 v240, v240, v241
	v_lshlrev_b32_e32 v240, 4, v240
	v_lshrrev_b32_e32 v241, 3, v164
	v_lshl_or_b32 v242, v241, 10, v240
	v_add_u32_e32 v243, 0x10000, v242
	v_bfe_u32 v244, v164, 5, 2
	v_lshlrev_b32_e32 v244, 3, v244
	v_bfe_u32 v245, v164, 7, 1
	v_lshl_or_b32 v244, v245, 2, v244
	v_bfe_u32 v245, v164, 3, 2
	v_or_b32_e32 v244, v244, v245
	v_bfe_u32 v245, v164, 8, 1
	v_lshl_or_b32 v247, v245, 5, v244
	v_lshl_or_b32 v244, v247, 10, v240
	v_add_u32_e32 v245, 0x10000, v244
	v_and_b32_e32 v246, 15, v164
	v_bfe_u32 v247, v164, 4, 2
	v_bfe_u32 v248, v164, 1, 3
	v_xor_b32_e32 v247, v247, v248
	v_lshlrev_b32_e32 v247, 4, v247
	v_lshl_or_b32 v246, v246, 7, v247
	v_mov_b32_e32 v168, v244
	v_and_or_b32 v4, v0, s7, v11
	s_movk_i32 s7, 0xe0
	s_lshr_b32 s18, s20, 6
	s_lshr_b32 s5, s20, 8
	v_and_or_b32 v0, v0, s7, v3
	s_lshl_b32 s7, s18, 10
	s_add_u32 s8, s58, 0x18800000
	s_addc_u32 s9, s59, 0
	s_add_i32 s3, s3, s4
	s_sext_i32_i16 s4, s3
	s_bfe_u32 s4, s4, 0x5001a
	s_add_i32 s4, s3, s4
	s_sext_i32_i16 s16, s4
	s_and_b32 s4, s4, 0xffe0
	s_sub_i32 s3, s3, s4
	s_bfe_i32 s4, s3, 0x80000
	s_bfe_u32 s4, s4, 0x3000c
	s_add_i32 s17, s3, s4
	s_bfe_i32 s4, s17, 0x80000
	s_and_b32 s17, s17, 0xf8
	s_ashr_i32 s16, s16, 5
	s_sub_i32 s3, s3, s17
	s_lshl_b32 s16, s16, 3
	s_sext_i32_i16 s4, s4
	s_sext_i32_i8 s3, s3
	s_lshr_b32 s4, s4, 3
	s_add_i32 s46, s16, s3
	s_ashr_i32 s47, s46, 31
	s_bfe_i64 s[22:23], s[4:5], 0x100000
	s_lshl_b64 s[16:17], s[46:47], 18
	s_lshl_b64 s[22:23], s[22:23], 18
	s_add_u32 s50, s68, s22
	s_addc_u32 s51, s69, s23
	s_add_i32 s34, s7, 0
	s_add_i32 m0, s34, 0x10000
	v_mov_b32_e32 v172, v245
	global_load_lds_dwordx4 v168, s[50:51]
	s_add_i32 m0, s34, 0x12000
	s_add_u32 s22, s50, 0x20000
	global_load_lds_dwordx4 v172, s[50:51]
	s_addc_u32 s23, s51, 0
	s_add_i32 m0, s34, 0x14000
	v_mov_b32_e32 v166, v242
	global_load_lds_dwordx4 v168, s[22:23]
	s_add_i32 m0, s34, 0x16000
	s_add_u32 s48, s8, s16
	s_addc_u32 s49, s9, s17
	s_add_i32 s35, s34, 0x2000
	global_load_lds_dwordx4 v172, s[22:23]
	s_mov_b32 m0, s34
	s_add_u32 s16, s48, 0x20000
	v_mov_b32_e32 v170, v243
	global_load_lds_dwordx4 v166, s[48:49]
	s_mov_b32 m0, s35
	s_addc_u32 s17, s49, 0
	s_add_i32 s58, s34, 0x4000
	global_load_lds_dwordx4 v170, s[48:49]
	s_mov_b32 m0, s58
	s_add_i32 s59, s34, 0x6000
	global_load_lds_dwordx4 v166, s[16:17]
	s_mov_b32 m0, s59
	v_mov_b32_e32 v0, 0
	global_load_lds_dwordx4 v170, s[16:17]
	v_mov_b32_e32 v169, v0
	v_mov_b32_e32 v173, v0
	v_mov_b32_e32 v167, v0
	v_mov_b32_e32 v171, v0
	s_cmp_eq_u32 s5, 1
	v_lshl_add_u64 v[8:9], s[50:51], 0, v[168:169]
	v_lshl_add_u64 v[6:7], s[50:51], 0, v[172:173]
	v_lshl_add_u64 v[2:3], s[48:49], 0, v[166:167]
	s_cselect_b64 s[16:17], -1, 0
	s_cmp_lg_u32 s5, 1
	v_lshl_add_u64 v[4:5], s[48:49], 0, v[170:171]
	s_cbranch_scc1 .LBB0_563
	s_barrier
;     __host__ __device__ bool next(int i, Unit& u) const { if (!so.next(i >> 1, u)) return false; u.seg = i & 1; return true; }
; #define PG8_WAIT_V(n) asm volatile("s_waitcnt vmcnt(" #n ")" ::: "memory")
; template <class Epi, class Sched, bool ALIGN_EPI = false, bool SP2 = false>
; __device__ __forceinline__ void gemm_phase(PG8_LAS unsigned char* lds, const Gemm g, const Sched& S, const Epi& E) {
;     ...
;     for (int i = 0; i < 2; ++i) { int R, C; stage_rc(tid * 16 + i * 8192, R, C); const int Rb = Epi::PERM ? ((R & ~31) + perm32(R & 31)) : R;
;         voffA[i] = (unsigned)(R * K + C) * 2u; voffB[i] = (unsigned)(Rb * K + C) * 2u; }
;     const size_t kstep = (size_t)(BK * 2);
;     const size_t hstep = (size_t)HALF * K * 2;
;     const size_t tstep = 2 * hstep;
;     const unsigned ldsw = (unsigned)wid * 1024u;
;     const int aoff = lds_byte(wr * 64 + fr, fq * 8), boff = lds_byte(wc * 32 + fr, fq * 8);
;     ...
;     Unit cur, nxt; int ui = 0;
;     if (!S.next(0, cur)) return;
;     f32x4 acc[2][2][4][2];
; #pragma unroll
;     for (int a = 0; a < 2; ++a)
; #pragma unroll
;         for (int b = 0; b < 2; ++b)
; #pragma unroll
;             for (int m = 0; m < 4; ++m)
; #pragma unroll
;                 for (int n = 0; n < 2; ++n) acc[a][b][m][n] = (f32x4){0.f, 0.f, 0.f, 0.f};
;     bf16x8 At[4][2], B0[2][2], B1[2][2];
;     const char* cA = (const char*)(cur.seg ? g.A1 : g.A0) + (size_t)cur.pm * tstep; const char* cB = (const char*)(cur.seg ? g.B1 : g.B0) + (size_t)cur.pn * tstep;
;     S.a_ready(cur);
;     if constexpr (SP2) {
;         PG8_STAGE(PG8_SB(0, 0), cB, voffB); PG8_STAGE(PG8_SB(0, 1), cB + hstep, voffB); PG8_STAGE(PG8_SA(0, 0), cA, voffA); PG8_STAGE(PG8_SA(0, 1), cA + hstep, voffA);
;         if (wr == 1) PG8_BAR;
;         PG8_WAIT_V(2); PG8_BAR;
;         PG8_STAGE(PG8_SB(1, 0), cB + kstep, voffB); PG8_STAGE(PG8_SA(1, 0), cA + kstep, voffA); PG8_STAGE(PG8_SB(1, 1), cB + hstep + kstep, voffB);
;         PG8_WAIT_V(6); PG8_BAR;
;     } else {
;         PG8_STAGE(PG8_SB(0, 0), cB, voffB); PG8_STAGE(PG8_SA(0, 0), cA, voffA); PG8_STAGE(PG8_SB(0, 1), cB + hstep, voffB); PG8_STAGE(PG8_SA(0, 1), cA + hstep, voffA);
;         if (wr == 1) PG8_BAR;
;         PG8_WAIT_V(4); PG8_BAR;
;         PG8_STAGE(PG8_SB(1, 0), cB + kstep, voffB); PG8_STAGE(PG8_SA(1, 0), cA + kstep, voffA); PG8_STAGE(PG8_SB(1, 1), cB + hstep + kstep, voffB);
;         PG8_WAIT_V(6); PG8_BAR;
.LBB0_563:
	s_sext_i32_i8 s3, s4
	s_lshl_b32 s4, s18, 5
	s_mov_b64 s[18:19], 0x80
	s_and_b32 s22, s4, 0x60
	s_add_i32 m0, s34, 0x18000
	v_lshl_add_u64 v[8:9], v[8:9], 0, s[18:19]
	s_lshl_b32 s21, s5, 13
	s_lshl_b32 s23, s22, 7
	s_waitcnt vmcnt(2)
	s_barrier
	global_load_lds_dwordx4 v[8:9], off
	v_lshl_add_u64 v[6:7], v[6:7], 0, s[18:19]
	s_add_i32 m0, s34, 0x1a000
	s_add_i32 s72, s34, 0x8000
	s_add_i32 s73, s34, 0xa000
	v_and_b32_e32 v14, 15, v164
	global_load_lds_dwordx4 v[6:7], off
	v_lshl_add_u64 v[2:3], v[2:3], 0, s[18:19]
	s_mov_b32 m0, s72
	s_add_u32 s4, s50, 0x20080
	v_lshl_or_b32 v182, s5, 6, v14
	global_load_lds_dwordx4 v[2:3], off
	v_lshl_add_u64 v[2:3], v[4:5], 0, s[18:19]
	s_mov_b32 m0, s73
	s_addc_u32 s5, s51, 0
	global_load_lds_dwordx4 v[2:3], off
	s_add_i32 m0, s34, 0x1c000
	v_lshl_add_u64 v[2:3], s[4:5], 0, v[168:169]
	global_load_lds_dwordx4 v[2:3], off
	v_lshl_add_u64 v[2:3], s[4:5], 0, v[172:173]
	s_add_i32 m0, s34, 0x1e000
	v_lshlrev_b32_e32 v4, 2, v164
	global_load_lds_dwordx4 v[2:3], off
	v_lshlrev_b32_e32 v2, 1, v12
	v_lshl_or_b32 v3, v14, 6, v2
	v_and_b32_e32 v4, 32, v4
	v_or_b32_e32 v5, s21, v246
	v_lshlrev_b32_e32 v3, 6, v164
	s_movk_i32 s4, 0x3c0
	v_and_or_b32 v2, v3, s4, v2
	v_or_b32_e32 v183, s23, v246
	v_lshlrev_b32_e32 v2, 7, v164
	v_and_b32_e32 v2, 0x1c000, v2
	v_lshlrev_b32_e32 v3, 10, v11
	v_or3_b32 v2, v1, v2, v3
	v_mov_b32_e32 v174, v242
	v_lshlrev_b32_e32 v2, 3, v13
	v_and_b32_e32 v2, 0x3c000, v2
	s_waitcnt vmcnt(6)
	v_or3_b32 v1, v1, v2, v3
	v_mov_b32_e32 v2, v0
	v_mov_b32_e32 v3, v0
	s_cmpk_lt_u32 s20, 0x100
	v_or_b32_e32 v184, s22, v12
	v_mov_b32_e32 v176, v243
	v_mov_b32_e32 v1, v0
	v_add_u32_e32 v185, 0, v5
	v_xor_b32_e32 v251, 64, v185
	v_mov_b64_e32 v[6:7], v[2:3]
	v_mov_b64_e32 v[10:11], v[2:3]
	v_mov_b64_e32 v[14:15], v[2:3]
	v_mov_b64_e32 v[18:19], v[2:3]
	v_mov_b64_e32 v[22:23], v[2:3]
	v_mov_b64_e32 v[26:27], v[2:3]
	v_mov_b64_e32 v[30:31], v[2:3]
	v_mov_b64_e32 v[34:35], v[2:3]
	v_mov_b64_e32 v[38:39], v[2:3]
	v_mov_b64_e32 v[42:43], v[2:3]
	v_mov_b64_e32 v[46:47], v[2:3]
	v_mov_b64_e32 v[50:51], v[2:3]
	v_mov_b64_e32 v[54:55], v[2:3]
	v_mov_b64_e32 v[58:59], v[2:3]
	v_mov_b64_e32 v[62:63], v[2:3]
	v_mov_b64_e32 v[66:67], v[2:3]
	v_mov_b64_e32 v[70:71], v[2:3]
	v_mov_b64_e32 v[74:75], v[2:3]
	v_mov_b64_e32 v[78:79], v[2:3]
	v_mov_b64_e32 v[82:83], v[2:3]
	v_mov_b64_e32 v[86:87], v[2:3]
	v_mov_b64_e32 v[90:91], v[2:3]
	v_mov_b64_e32 v[94:95], v[2:3]
	v_mov_b64_e32 v[98:99], v[2:3]
	v_mov_b64_e32 v[102:103], v[2:3]
	v_mov_b64_e32 v[106:107], v[2:3]
	v_mov_b64_e32 v[110:111], v[2:3]
	v_mov_b64_e32 v[114:115], v[2:3]
	v_mov_b64_e32 v[118:119], v[2:3]
	v_mov_b64_e32 v[122:123], v[2:3]
	v_mov_b64_e32 v[126:127], v[2:3]
	v_mov_b64_e32 v[130:131], v[2:3]
	s_cselect_b64 s[20:21], -1, 0
	v_mov_b32_e32 v175, v0
	v_mov_b32_e32 v177, v0
	s_mov_b32 s30, 0
	v_mov_b64_e32 v[178:179], 0x200
	v_mov_b64_e32 v[180:181], 0x1ff
	s_add_i32 s74, 0, 0x10000
	s_add_i32 s75, 0, 0x14000
	s_mov_b64 s[22:23], 0x80000
	s_mov_b32 s76, 0x80000
	s_mov_b64 s[24:25], 0x90000
	s_mov_b32 s77, 0x90000
	s_mov_b64 s[26:27], 0xa0000
	s_mov_b32 s78, 0xa0000
	s_mov_b64 s[36:37], 0xb0000
	s_mov_b32 s79, 0xb0000
	v_mov_b64_e32 v[4:5], v[0:1]
	v_mov_b64_e32 v[8:9], v[0:1]
	v_mov_b64_e32 v[12:13], v[0:1]
	v_mov_b64_e32 v[16:17], v[0:1]
	v_mov_b64_e32 v[20:21], v[0:1]
	v_mov_b64_e32 v[24:25], v[0:1]
	v_mov_b64_e32 v[28:29], v[0:1]
	v_mov_b64_e32 v[32:33], v[0:1]
	v_mov_b64_e32 v[36:37], v[0:1]
	v_mov_b64_e32 v[40:41], v[0:1]
	v_mov_b64_e32 v[44:45], v[0:1]
	v_mov_b64_e32 v[48:49], v[0:1]
	v_mov_b64_e32 v[52:53], v[0:1]
	v_mov_b64_e32 v[56:57], v[0:1]
	v_mov_b64_e32 v[60:61], v[0:1]
	v_mov_b64_e32 v[64:65], v[0:1]
	v_mov_b64_e32 v[68:69], v[0:1]
	v_mov_b64_e32 v[72:73], v[0:1]
	v_mov_b64_e32 v[76:77], v[0:1]
	v_mov_b64_e32 v[80:81], v[0:1]
	v_mov_b64_e32 v[84:85], v[0:1]
	v_mov_b64_e32 v[88:89], v[0:1]
	v_mov_b64_e32 v[92:93], v[0:1]
	v_mov_b64_e32 v[96:97], v[0:1]
	v_mov_b64_e32 v[100:101], v[0:1]
	v_mov_b64_e32 v[104:105], v[0:1]
	v_mov_b64_e32 v[108:109], v[0:1]
	v_mov_b64_e32 v[112:113], v[0:1]
	v_mov_b64_e32 v[116:117], v[0:1]
	v_mov_b64_e32 v[120:121], v[0:1]
	v_mov_b64_e32 v[124:125], v[0:1]
	v_mov_b64_e32 v[128:129], v[0:1]
	s_mov_b32 s80, 0
	s_barrier
	s_branch .LBB0_566

; #define PG8_STAGE(bufoff, gbase, voff) do { _Pragma("unroll") for (int _i = 0; _i < 2; ++_i) \
;         __builtin_amdgcn_global_load_lds((const unsigned*)((const char*)(gbase) + (voff)[_i]), (PG8_LAS unsigned*)(lds + (bufoff) + ldsw + _i * 8192), 16, 0, 0); } while (0)
; #define PG8_LDA(dst, b, h) do { _Pragma("unroll") for (int m = 0; m < 4; ++m) _Pragma("unroll") for (int k = 0; k < 2; ++k) dst[m][k] = *(const PG8_LAS bf16x8*)(lds + PG8_SA(b, h) + aoff + m * 2048 + k * 1024); } while (0)
; #define PG8_LDB(dst, b, h) do { _Pragma("unroll") for (int n = 0; n < 2; ++n) _Pragma("unroll") for (int k = 0; k < 2; ++k) dst[n][k] = *(const PG8_LAS bf16x8*)(lds + PG8_SB(b, h) + boff + n * 2048 + k * 1024); } while (0)
; #define PG8_MMA(ai, bj, At, Bt) do { __builtin_amdgcn_s_setprio(1); _Pragma("unroll") for (int m = 0; m < 4; ++m) _Pragma("unroll") for (int n = 0; n < 2; ++n) _Pragma("unroll") for (int k = 0; k < 2; ++k) \
;         acc[ai][bj][m][n] = __builtin_amdgcn_mfma_f32_16x16x32_bf16(Bt[n][k], At[m][k], acc[ai][bj][m][n], 0, 0, 0); __builtin_amdgcn_s_setprio(0); } while (0)
; #define PG8_WAIT_V(n) asm volatile("s_waitcnt vmcnt(" #n ")" ::: "memory")
; #define PG8_WAIT_L(n) asm volatile("s_waitcnt lgkmcnt(" #n ")" ::: "memory")
; #define PG8_BAR __builtin_amdgcn_s_barrier()
; #define PG8_SCHED __builtin_amdgcn_sched_barrier(0)
; template <class Epi, class Sched, bool ALIGN_EPI = false, bool SP2 = false>
; __device__ __forceinline__ void gemm_phase(PG8_LAS unsigned char* lds, const Gemm g, const Sched& S, const Epi& E) {
;     ...
;             PG8_LDB(B0, 0, 0); PG8_LDB(B1, 0, 1); PG8_SCHED; PG8_LDA(At, 0, 0); PG8_STAGE(PG8_SA(1, 1), a1 + hstep, voffA);
;             PG8_WAIT_V(8); PG8_WAIT_L(0); PG8_BAR; PG8_MMA(0, 0, At, B0); PG8_MMA(0, 1, At, B1); PG8_BAR; PG8_SCHED;
;             PG8_LDA(At, 0, 1); PG8_STAGE(PG8_SB(0, 0), b2, voffB); PG8_STAGE(PG8_SB(0, 1), b2 + hstep, voffB); PG8_STAGE(PG8_SA(0, 0), a2, voffA);
;             PG8_WAIT_V(8); PG8_WAIT_L(0); PG8_BAR; PG8_MMA(1, 0, At, B0); PG8_MMA(1, 1, At, B1); PG8_BAR; PG8_SCHED;
.LBB0_573:
	v_add_u32_e32 v1, s74, v183
	v_xor_b32_e32 v252, 64, v1
	ds_read_b128 v[132:135], v1
	ds_read_b128 v[136:139], v252
	ds_read_b128 v[140:143], v1 offset:2048
	ds_read_b128 v[144:147], v252 offset:2048
	v_add_u32_e32 v1, s75, v183
	v_xor_b32_e32 v252, 64, v1
	ds_read_b128 v[148:151], v1
	ds_read_b128 v[152:155], v252
	ds_read_b128 v[156:159], v1 offset:2048
	ds_read_b128 v[160:163], v252 offset:2048
	s_add_u32 s50, s48, 0xfffe0080
	s_addc_u32 s51, s49, -1
	s_cmp_eq_u32 s84, 4
	s_cselect_b32 s53, s31, s51
	s_cselect_b32 s52, s39, s50
	s_cselect_b32 s51, s41, s83
	s_cselect_b32 s50, s47, s82
	s_add_i32 m0, s34, 0xc000
	ds_read_b128 v[186:189], v185
	ds_read_b128 v[190:193], v251
	ds_read_b128 v[194:197], v185 offset:2048
	ds_read_b128 v[198:201], v251 offset:2048
	ds_read_b128 v[202:205], v185 offset:4096
	ds_read_b128 v[206:209], v251 offset:4096
	ds_read_b128 v[210:213], v185 offset:6144
	ds_read_b128 v[214:217], v251 offset:6144
	global_load_lds_dwordx4 v174, s[48:49]
	s_add_i32 m0, s34, 0xe000
	s_nop 0
	global_load_lds_dwordx4 v176, s[48:49]
	s_waitcnt vmcnt(8)
	s_waitcnt lgkmcnt(0)
	s_barrier
	s_setprio 1
	s_waitcnt lgkmcnt(0)
	v_mfma_f32_16x16x32_bf16 v[128:131], v[132:135], v[186:189], v[128:131]
	v_mfma_f32_16x16x32_bf16 v[124:127], v[140:143], v[186:189], v[124:127]
	v_mfma_f32_16x16x32_bf16 v[120:123], v[132:135], v[194:197], v[120:123]
	v_mfma_f32_16x16x32_bf16 v[116:119], v[140:143], v[194:197], v[116:119]
	v_mfma_f32_16x16x32_bf16 v[112:115], v[132:135], v[202:205], v[112:115]
	v_mfma_f32_16x16x32_bf16 v[108:111], v[140:143], v[202:205], v[108:111]
	v_mfma_f32_16x16x32_bf16 v[104:107], v[132:135], v[210:213], v[104:107]
	v_mfma_f32_16x16x32_bf16 v[100:103], v[140:143], v[210:213], v[100:103]
	v_mfma_f32_16x16x32_bf16 v[128:131], v[136:139], v[190:193], v[128:131]
	v_mfma_f32_16x16x32_bf16 v[124:127], v[144:147], v[190:193], v[124:127]
	v_mfma_f32_16x16x32_bf16 v[120:123], v[136:139], v[198:201], v[120:123]
	v_mfma_f32_16x16x32_bf16 v[116:119], v[144:147], v[198:201], v[116:119]
	v_mfma_f32_16x16x32_bf16 v[112:115], v[136:139], v[206:209], v[112:115]
	v_mfma_f32_16x16x32_bf16 v[108:111], v[144:147], v[206:209], v[108:111]
	v_mfma_f32_16x16x32_bf16 v[104:107], v[136:139], v[214:217], v[104:107]
	v_mfma_f32_16x16x32_bf16 v[100:103], v[144:147], v[214:217], v[100:103]
	s_setprio 0
	s_setprio 1
	v_mfma_f32_16x16x32_bf16 v[96:99], v[148:151], v[186:189], v[96:99]
	v_mfma_f32_16x16x32_bf16 v[92:95], v[156:159], v[186:189], v[92:95]
	v_mfma_f32_16x16x32_bf16 v[88:91], v[148:151], v[194:197], v[88:91]
	v_mfma_f32_16x16x32_bf16 v[84:87], v[156:159], v[194:197], v[84:87]
	v_mfma_f32_16x16x32_bf16 v[80:83], v[148:151], v[202:205], v[80:83]
	v_mfma_f32_16x16x32_bf16 v[76:79], v[156:159], v[202:205], v[76:79]
	v_mfma_f32_16x16x32_bf16 v[72:75], v[148:151], v[210:213], v[72:75]
	v_mfma_f32_16x16x32_bf16 v[68:71], v[156:159], v[210:213], v[68:71]
	v_mfma_f32_16x16x32_bf16 v[96:99], v[152:155], v[190:193], v[96:99]
	v_mfma_f32_16x16x32_bf16 v[92:95], v[160:163], v[190:193], v[92:95]
	v_mfma_f32_16x16x32_bf16 v[88:91], v[152:155], v[198:201], v[88:91]
	v_mfma_f32_16x16x32_bf16 v[84:87], v[160:163], v[198:201], v[84:87]
	v_mfma_f32_16x16x32_bf16 v[80:83], v[152:155], v[206:209], v[80:83]
	v_mfma_f32_16x16x32_bf16 v[76:79], v[160:163], v[206:209], v[76:79]
	v_mfma_f32_16x16x32_bf16 v[72:75], v[152:155], v[214:217], v[72:75]
	v_mfma_f32_16x16x32_bf16 v[68:71], v[160:163], v[214:217], v[68:71]
	s_setprio 0
	s_barrier
	s_add_i32 s85, s74, s7
	s_mov_b32 m0, s85
	ds_read_b128 v[186:189], v185 offset:16384
	ds_read_b128 v[190:193], v251 offset:16384
	ds_read_b128 v[194:197], v185 offset:18432
	ds_read_b128 v[198:201], v251 offset:18432
	ds_read_b128 v[202:205], v185 offset:20480
	ds_read_b128 v[206:209], v251 offset:20480
	ds_read_b128 v[210:213], v185 offset:22528
	ds_read_b128 v[214:217], v251 offset:22528
	global_load_lds_dwordx4 v168, s[50:51]
	s_add_i32 m0, s85, 0x2000
	s_add_u32 s86, s50, 0x20000
	s_addc_u32 s87, s51, 0
	s_add_i32 s85, s75, s7
	global_load_lds_dwordx4 v172, s[50:51]
	s_mov_b32 m0, s85
	s_nop 0
	global_load_lds_dwordx4 v168, s[86:87]
	s_add_i32 m0, s85, 0x2000
	s_nop 0
	global_load_lds_dwordx4 v172, s[86:87]
	s_mov_b32 m0, s34
	s_nop 0
	global_load_lds_dwordx4 v166, s[52:53]
	s_mov_b32 m0, s35
	s_nop 0
	global_load_lds_dwordx4 v170, s[52:53]
	s_waitcnt vmcnt(8)
	s_waitcnt lgkmcnt(0)
	s_barrier
	s_setprio 1
	s_waitcnt lgkmcnt(0)
	v_mfma_f32_16x16x32_bf16 v[64:67], v[132:135], v[186:189], v[64:67]
	v_mfma_f32_16x16x32_bf16 v[60:63], v[140:143], v[186:189], v[60:63]
	v_mfma_f32_16x16x32_bf16 v[56:59], v[132:135], v[194:197], v[56:59]
	v_mfma_f32_16x16x32_bf16 v[52:55], v[140:143], v[194:197], v[52:55]
	v_mfma_f32_16x16x32_bf16 v[48:51], v[132:135], v[202:205], v[48:51]
	v_mfma_f32_16x16x32_bf16 v[44:47], v[140:143], v[202:205], v[44:47]
	v_mfma_f32_16x16x32_bf16 v[40:43], v[132:135], v[210:213], v[40:43]
	v_mfma_f32_16x16x32_bf16 v[36:39], v[140:143], v[210:213], v[36:39]
	v_mfma_f32_16x16x32_bf16 v[64:67], v[136:139], v[190:193], v[64:67]
	v_mfma_f32_16x16x32_bf16 v[60:63], v[144:147], v[190:193], v[60:63]
	v_mfma_f32_16x16x32_bf16 v[56:59], v[136:139], v[198:201], v[56:59]
	v_mfma_f32_16x16x32_bf16 v[52:55], v[144:147], v[198:201], v[52:55]
	v_mfma_f32_16x16x32_bf16 v[48:51], v[136:139], v[206:209], v[48:51]
	v_mfma_f32_16x16x32_bf16 v[44:47], v[144:147], v[206:209], v[44:47]
	v_mfma_f32_16x16x32_bf16 v[40:43], v[136:139], v[214:217], v[40:43]
	v_mfma_f32_16x16x32_bf16 v[36:39], v[144:147], v[214:217], v[36:39]
	s_setprio 0
	s_setprio 1
	v_mfma_f32_16x16x32_bf16 v[32:35], v[148:151], v[186:189], v[32:35]
	v_mfma_f32_16x16x32_bf16 v[28:31], v[156:159], v[186:189], v[28:31]
	v_mfma_f32_16x16x32_bf16 v[24:27], v[148:151], v[194:197], v[24:27]
	v_mfma_f32_16x16x32_bf16 v[20:23], v[156:159], v[194:197], v[20:23]
	v_mfma_f32_16x16x32_bf16 v[16:19], v[148:151], v[202:205], v[16:19]
	v_mfma_f32_16x16x32_bf16 v[12:15], v[156:159], v[202:205], v[12:15]
	v_mfma_f32_16x16x32_bf16 v[8:11], v[148:151], v[210:213], v[8:11]
	v_mfma_f32_16x16x32_bf16 v[2:5], v[156:159], v[210:213], v[4:7]
	v_mfma_f32_16x16x32_bf16 v[32:35], v[152:155], v[190:193], v[32:35]
	v_mfma_f32_16x16x32_bf16 v[28:31], v[160:163], v[190:193], v[28:31]
	v_mfma_f32_16x16x32_bf16 v[24:27], v[152:155], v[198:201], v[24:27]
	v_mfma_f32_16x16x32_bf16 v[20:23], v[160:163], v[198:201], v[20:23]
	v_mfma_f32_16x16x32_bf16 v[16:19], v[152:155], v[206:209], v[16:19]
	v_mfma_f32_16x16x32_bf16 v[12:15], v[160:163], v[206:209], v[12:15]
	v_mfma_f32_16x16x32_bf16 v[8:11], v[152:155], v[214:217], v[8:11]
	v_mfma_f32_16x16x32_bf16 v[2:5], v[160:163], v[214:217], v[2:5]
	s_setprio 0
	s_barrier
; #define PG8_STAGE(bufoff, gbase, voff) do { _Pragma("unroll") for (int _i = 0; _i < 2; ++_i) \
;         __builtin_amdgcn_global_load_lds((const unsigned*)((const char*)(gbase) + (voff)[_i]), (PG8_LAS unsigned*)(lds + (bufoff) + ldsw + _i * 8192), 16, 0, 0); } while (0)
; #define PG8_LDA(dst, b, h) do { _Pragma("unroll") for (int m = 0; m < 4; ++m) _Pragma("unroll") for (int k = 0; k < 2; ++k) dst[m][k] = *(const PG8_LAS bf16x8*)(lds + PG8_SA(b, h) + aoff + m * 2048 + k * 1024); } while (0)
; #define PG8_LDB(dst, b, h) do { _Pragma("unroll") for (int n = 0; n < 2; ++n) _Pragma("unroll") for (int k = 0; k < 2; ++k) dst[n][k] = *(const PG8_LAS bf16x8*)(lds + PG8_SB(b, h) + boff + n * 2048 + k * 1024); } while (0)
; #define PG8_MMA(ai, bj, At, Bt) do { __builtin_amdgcn_s_setprio(1); _Pragma("unroll") for (int m = 0; m < 4; ++m) _Pragma("unroll") for (int n = 0; n < 2; ++n) _Pragma("unroll") for (int k = 0; k < 2; ++k) \
;         acc[ai][bj][m][n] = __builtin_amdgcn_mfma_f32_16x16x32_bf16(Bt[n][k], At[m][k], acc[ai][bj][m][n], 0, 0, 0); __builtin_amdgcn_s_setprio(0); } while (0)
; #define PG8_WAIT_V(n) asm volatile("s_waitcnt vmcnt(" #n ")" ::: "memory")
; #define PG8_WAIT_L(n) asm volatile("s_waitcnt lgkmcnt(" #n ")" ::: "memory")
; template <class Epi, class Sched, bool ALIGN_EPI = false, bool SP2 = false>
; __device__ __forceinline__ void gemm_phase(PG8_LAS unsigned char* lds, const Gemm g, const Sched& S, const Epi& E) {
;     ...
;         for (int t = 0; t < nt; t += 2) {
;             const bool last = (t == nt - 2);
;             const char* a1 = cA + (size_t)(t + 1) * kstep;
;             const char* a2 = last ? nA : cA + (size_t)(t + 2) * kstep; const char* b2 = last ? nB : cB + (size_t)(t + 2) * kstep;
;             const char* a3 = a2 + kstep; const char* b3 = b2 + kstep;
;             if (last && has_next) S.a_ready(nxt);
;     ...
;             PG8_LDB(B0, 1, 0); PG8_LDB(B1, 1, 1); PG8_SCHED; PG8_LDA(At, 1, 0); PG8_STAGE(PG8_SA(0, 1), a2 + hstep, voffA);
;             PG8_WAIT_V(8); PG8_WAIT_L(0); PG8_BAR; PG8_MMA(0, 0, At, B0); PG8_MMA(0, 1, At, B1); PG8_BAR; PG8_SCHED;
;             PG8_LDA(At, 1, 1); PG8_STAGE(PG8_SB(1, 0), b3, voffB); PG8_STAGE(PG8_SB(1, 1), b3 + hstep, voffB); PG8_STAGE(PG8_SA(1, 0), a3, voffA);
;             PG8_WAIT_V(8); PG8_WAIT_L(0); PG8_BAR; PG8_MMA(1, 0, At, B0); PG8_MMA(1, 1, At, B1); PG8_BAR; PG8_SCHED;
	s_add_i32 s85, 0, 0x18000
	v_add_u32_e32 v1, s85, v183
	v_xor_b32_e32 v252, 64, v1
	s_add_i32 s86, 0, 0x1c000
	ds_read_b128 v[132:135], v1
	ds_read_b128 v[136:139], v252
	ds_read_b128 v[140:143], v1 offset:2048
	ds_read_b128 v[144:147], v252 offset:2048
	v_add_u32_e32 v1, s86, v183
	v_xor_b32_e32 v252, 64, v1
	ds_read_b128 v[148:151], v1
	ds_read_b128 v[152:155], v252
	ds_read_b128 v[156:159], v1 offset:2048
	ds_read_b128 v[160:163], v252 offset:2048
	s_add_u32 s52, s52, 0x20000
	s_addc_u32 s53, s53, 0
	s_mov_b32 m0, s58
	ds_read_b128 v[186:189], v185 offset:32768
	ds_read_b128 v[190:193], v251 offset:32768
	ds_read_b128 v[194:197], v185 offset:34816
	ds_read_b128 v[198:201], v251 offset:34816
	ds_read_b128 v[202:205], v185 offset:36864
	ds_read_b128 v[206:209], v251 offset:36864
	ds_read_b128 v[210:213], v185 offset:38912
	ds_read_b128 v[214:217], v251 offset:38912
	global_load_lds_dwordx4 v166, s[52:53]
	s_mov_b32 m0, s59
	s_nop 0
	global_load_lds_dwordx4 v170, s[52:53]
	s_add_u32 s100, s50, 0x80
	s_addc_u32 s101, s51, 0
	s_sub_u32 s98, s52, 0x1ff80
	s_subb_u32 s99, s53, 0
	s_waitcnt vmcnt(8)
	s_waitcnt lgkmcnt(0)
	s_barrier
	s_setprio 1
	s_waitcnt lgkmcnt(0)
	v_mfma_f32_16x16x32_bf16 v[128:131], v[132:135], v[186:189], v[128:131]
	v_mfma_f32_16x16x32_bf16 v[124:127], v[140:143], v[186:189], v[124:127]
	v_mfma_f32_16x16x32_bf16 v[120:123], v[132:135], v[194:197], v[120:123]
	v_mfma_f32_16x16x32_bf16 v[116:119], v[140:143], v[194:197], v[116:119]
	v_mfma_f32_16x16x32_bf16 v[112:115], v[132:135], v[202:205], v[112:115]
	v_mfma_f32_16x16x32_bf16 v[108:111], v[140:143], v[202:205], v[108:111]
	v_mfma_f32_16x16x32_bf16 v[104:107], v[132:135], v[210:213], v[104:107]
	v_mfma_f32_16x16x32_bf16 v[100:103], v[140:143], v[210:213], v[100:103]
	v_mfma_f32_16x16x32_bf16 v[128:131], v[136:139], v[190:193], v[128:131]
	v_mfma_f32_16x16x32_bf16 v[124:127], v[144:147], v[190:193], v[124:127]
	v_mfma_f32_16x16x32_bf16 v[120:123], v[136:139], v[198:201], v[120:123]
	v_mfma_f32_16x16x32_bf16 v[116:119], v[144:147], v[198:201], v[116:119]
	v_mfma_f32_16x16x32_bf16 v[112:115], v[136:139], v[206:209], v[112:115]
	v_mfma_f32_16x16x32_bf16 v[108:111], v[144:147], v[206:209], v[108:111]
	v_mfma_f32_16x16x32_bf16 v[104:107], v[136:139], v[214:217], v[104:107]
	v_mfma_f32_16x16x32_bf16 v[100:103], v[144:147], v[214:217], v[100:103]
	s_setprio 0
	s_setprio 1
	v_mfma_f32_16x16x32_bf16 v[96:99], v[148:151], v[186:189], v[96:99]
	v_mfma_f32_16x16x32_bf16 v[92:95], v[156:159], v[186:189], v[92:95]
	v_mfma_f32_16x16x32_bf16 v[88:91], v[148:151], v[194:197], v[88:91]
	v_mfma_f32_16x16x32_bf16 v[84:87], v[156:159], v[194:197], v[84:87]
	v_mfma_f32_16x16x32_bf16 v[80:83], v[148:151], v[202:205], v[80:83]
	v_mfma_f32_16x16x32_bf16 v[76:79], v[156:159], v[202:205], v[76:79]
	v_mfma_f32_16x16x32_bf16 v[72:75], v[148:151], v[210:213], v[72:75]
	v_mfma_f32_16x16x32_bf16 v[68:71], v[156:159], v[210:213], v[68:71]
	v_mfma_f32_16x16x32_bf16 v[96:99], v[152:155], v[190:193], v[96:99]
	v_mfma_f32_16x16x32_bf16 v[92:95], v[160:163], v[190:193], v[92:95]
	v_mfma_f32_16x16x32_bf16 v[88:91], v[152:155], v[198:201], v[88:91]
	v_mfma_f32_16x16x32_bf16 v[84:87], v[160:163], v[198:201], v[84:87]
	v_mfma_f32_16x16x32_bf16 v[80:83], v[152:155], v[206:209], v[80:83]
	v_mfma_f32_16x16x32_bf16 v[76:79], v[160:163], v[206:209], v[76:79]
	v_mfma_f32_16x16x32_bf16 v[72:75], v[152:155], v[214:217], v[72:75]
	v_mfma_f32_16x16x32_bf16 v[68:71], v[160:163], v[214:217], v[68:71]
	s_setprio 0
	s_barrier
	s_add_i32 s52, s85, s7
	s_mov_b32 m0, s52
	ds_read_b128 v[186:189], v185 offset:49152
	ds_read_b128 v[190:193], v251 offset:49152
	ds_read_b128 v[194:197], v185 offset:51200
	ds_read_b128 v[198:201], v251 offset:51200
	ds_read_b128 v[202:205], v185 offset:53248
	ds_read_b128 v[206:209], v251 offset:53248
	ds_read_b128 v[210:213], v185 offset:55296
	ds_read_b128 v[214:217], v251 offset:55296
	global_load_lds_dwordx4 v168, s[100:101]
	s_add_i32 m0, s52, 0x2000
	s_add_u32 s50, s50, 0x20080
	s_addc_u32 s51, s51, 0
	s_add_i32 s52, s86, s7
	global_load_lds_dwordx4 v172, s[100:101]
	s_mov_b32 m0, s52
	s_nop 0
	global_load_lds_dwordx4 v168, s[50:51]
	s_add_i32 m0, s52, 0x2000
	s_nop 0
	global_load_lds_dwordx4 v172, s[50:51]
	s_mov_b32 m0, s72
	s_nop 0
	global_load_lds_dwordx4 v166, s[98:99]
	s_mov_b32 m0, s73
	s_nop 0
	global_load_lds_dwordx4 v170, s[98:99]
	s_waitcnt vmcnt(8)
	s_waitcnt lgkmcnt(0)
	s_barrier
	s_setprio 1
	s_waitcnt lgkmcnt(0)
	v_mfma_f32_16x16x32_bf16 v[64:67], v[132:135], v[186:189], v[64:67]
	v_mfma_f32_16x16x32_bf16 v[60:63], v[140:143], v[186:189], v[60:63]
	v_mfma_f32_16x16x32_bf16 v[56:59], v[132:135], v[194:197], v[56:59]
	v_mfma_f32_16x16x32_bf16 v[52:55], v[140:143], v[194:197], v[52:55]
	v_mfma_f32_16x16x32_bf16 v[48:51], v[132:135], v[202:205], v[48:51]
	v_mfma_f32_16x16x32_bf16 v[44:47], v[140:143], v[202:205], v[44:47]
	v_mfma_f32_16x16x32_bf16 v[40:43], v[132:135], v[210:213], v[40:43]
	v_mfma_f32_16x16x32_bf16 v[36:39], v[140:143], v[210:213], v[36:39]
	v_mfma_f32_16x16x32_bf16 v[64:67], v[136:139], v[190:193], v[64:67]
	v_mfma_f32_16x16x32_bf16 v[60:63], v[144:147], v[190:193], v[60:63]
	v_mfma_f32_16x16x32_bf16 v[56:59], v[136:139], v[198:201], v[56:59]
	v_mfma_f32_16x16x32_bf16 v[52:55], v[144:147], v[198:201], v[52:55]
	v_mfma_f32_16x16x32_bf16 v[48:51], v[136:139], v[206:209], v[48:51]
	v_mfma_f32_16x16x32_bf16 v[44:47], v[144:147], v[206:209], v[44:47]
	v_mfma_f32_16x16x32_bf16 v[40:43], v[136:139], v[214:217], v[40:43]
	v_mfma_f32_16x16x32_bf16 v[36:39], v[144:147], v[214:217], v[36:39]
	s_setprio 0
	s_setprio 1
	v_mfma_f32_16x16x32_bf16 v[32:35], v[148:151], v[186:189], v[32:35]
	v_mfma_f32_16x16x32_bf16 v[28:31], v[156:159], v[186:189], v[28:31]
	v_mfma_f32_16x16x32_bf16 v[24:27], v[148:151], v[194:197], v[24:27]
	v_mfma_f32_16x16x32_bf16 v[20:23], v[156:159], v[194:197], v[20:23]
	v_mfma_f32_16x16x32_bf16 v[16:19], v[148:151], v[202:205], v[16:19]
	v_mfma_f32_16x16x32_bf16 v[12:15], v[156:159], v[202:205], v[12:15]
	v_mfma_f32_16x16x32_bf16 v[6:9], v[148:151], v[210:213], v[8:11]
	v_mfma_f32_16x16x32_bf16 v[2:5], v[156:159], v[210:213], v[2:5]
	v_mfma_f32_16x16x32_bf16 v[32:35], v[152:155], v[190:193], v[32:35]
	v_mfma_f32_16x16x32_bf16 v[28:31], v[160:163], v[190:193], v[28:31]
	v_mfma_f32_16x16x32_bf16 v[24:27], v[152:155], v[198:201], v[24:27]
	v_mfma_f32_16x16x32_bf16 v[20:23], v[160:163], v[198:201], v[20:23]
	v_mfma_f32_16x16x32_bf16 v[16:19], v[152:155], v[206:209], v[16:19]
	v_mfma_f32_16x16x32_bf16 v[12:15], v[160:163], v[206:209], v[12:15]
	v_mfma_f32_16x16x32_bf16 v[8:11], v[152:155], v[214:217], v[6:9]
	v_mfma_f32_16x16x32_bf16 v[4:7], v[160:163], v[214:217], v[2:5]
	s_setprio 0
	s_barrier
	s_add_i32 s84, s84, 2
	s_add_u32 s48, s48, 0x100
	s_addc_u32 s49, s49, 0
	s_add_u32 s82, s82, 0x100
	s_addc_u32 s83, s83, 0
	s_cmp_gt_u32 s84, 5
	s_cbranch_scc0 .LBB0_573
	s_and_b64 vcc, exec, s[20:21]
	s_cbranch_vccz .LBB0_576
	s_barrier

;     __host__ __device__ bool next(int i, Unit& u) const { if (!so.next(i >> 1, u)) return false; u.seg = i & 1; return true; }
; #define PG8_WAIT_V(n) asm volatile("s_waitcnt vmcnt(" #n ")" ::: "memory")
; template <class Epi, class Sched, bool ALIGN_EPI = false, bool SP2 = false>
; __device__ __forceinline__ void gemm_phase(PG8_LAS unsigned char* lds, const Gemm g, const Sched& S, const Epi& E) {
;     ...
;     for (int i = 0; i < 2; ++i) { int R, C; stage_rc(tid * 16 + i * 8192, R, C); const int Rb = Epi::PERM ? ((R & ~31) + perm32(R & 31)) : R;
;         voffA[i] = (unsigned)(R * K + C) * 2u; voffB[i] = (unsigned)(Rb * K + C) * 2u; }
;     const size_t kstep = (size_t)(BK * 2);
;     const size_t hstep = (size_t)HALF * K * 2;
;     const size_t tstep = 2 * hstep;
;     const unsigned ldsw = (unsigned)wid * 1024u;
;     const int aoff = lds_byte(wr * 64 + fr, fq * 8), boff = lds_byte(wc * 32 + fr, fq * 8);
;     ...
;     Unit cur, nxt; int ui = 0;
;     if (!S.next(0, cur)) return;
;     f32x4 acc[2][2][4][2];
; #pragma unroll
;     for (int a = 0; a < 2; ++a)
; #pragma unroll
;         for (int b = 0; b < 2; ++b)
; #pragma unroll
;             for (int m = 0; m < 4; ++m)
; #pragma unroll
;                 for (int n = 0; n < 2; ++n) acc[a][b][m][n] = (f32x4){0.f, 0.f, 0.f, 0.f};
;     bf16x8 At[4][2], B0[2][2], B1[2][2];
;     const char* cA = (const char*)(cur.seg ? g.A1 : g.A0) + (size_t)cur.pm * tstep; const char* cB = (const char*)(cur.seg ? g.B1 : g.B0) + (size_t)cur.pn * tstep;
;     S.a_ready(cur);
;     if constexpr (SP2) {
;         PG8_STAGE(PG8_SB(0, 0), cB, voffB); PG8_STAGE(PG8_SB(0, 1), cB + hstep, voffB); PG8_STAGE(PG8_SA(0, 0), cA, voffA); PG8_STAGE(PG8_SA(0, 1), cA + hstep, voffA);
;         if (wr == 1) PG8_BAR;
;         PG8_WAIT_V(2); PG8_BAR;
;         PG8_STAGE(PG8_SB(1, 0), cB + kstep, voffB); PG8_STAGE(PG8_SA(1, 0), cA + kstep, voffA); PG8_STAGE(PG8_SB(1, 1), cB + hstep + kstep, voffB);
;         PG8_WAIT_V(6); PG8_BAR;
;     } else {
;         PG8_STAGE(PG8_SB(0, 0), cB, voffB); PG8_STAGE(PG8_SA(0, 0), cA, voffA); PG8_STAGE(PG8_SB(0, 1), cB + hstep, voffB); PG8_STAGE(PG8_SA(0, 1), cA + hstep, voffA);
;         if (wr == 1) PG8_BAR;
;         PG8_WAIT_V(4); PG8_BAR;
;         PG8_STAGE(PG8_SB(1, 0), cB + kstep, voffB); PG8_STAGE(PG8_SA(1, 0), cA + kstep, voffA); PG8_STAGE(PG8_SB(1, 1), cB + hstep + kstep, voffB);
;         PG8_WAIT_V(6); PG8_BAR;
.LBB0_668:
	s_add_i32 s4, s8, s4
	s_sext_i32_i16 s8, s4
	s_bfe_u32 s8, s8, 0x5001a
	s_add_i32 s8, s4, s8
	s_sext_i32_i16 s9, s8
	s_and_b32 s8, s8, 0xffe0
	s_sub_i32 s8, s4, s8
	s_bfe_i32 s4, s8, 0x80000
	s_bfe_u32 s4, s4, 0x3000c
	v_lshrrev_b32_e32 v2, 1, v164
	v_lshrrev_b32_e32 v3, 5, v164
	s_add_i32 s14, s8, s4
	v_and_b32_e32 v2, 24, v2
	v_and_b32_e32 v3, 4, v3
	v_bfe_u32 v4, v164, 2, 2
	s_bfe_i32 s4, s14, 0x80000
	s_and_b32 s14, s14, 0xf8
	v_lshlrev_b32_e32 v0, 4, v164
	v_and_b32_e32 v1, 32, v164
	v_bfe_u32 v10, v164, 2, 4
	v_or3_b32 v2, v3, v4, v2
	v_lshrrev_b32_e32 v3, 3, v164
	s_movk_i32 s7, 0x70
	s_ashr_i32 s9, s9, 5
	s_sub_i32 s8, s8, s14
	v_bitop3_b32 v8, v0, v1, 48 bitop3:0x6c
	v_and_b32_e32 v9, 64, v164
	v_and_or_b32 v4, v3, s7, v10
	s_movk_i32 s7, 0x60
	v_add_u32_e32 v11, 0x2000, v0
	s_lshl_b32 s9, s9, 3
	s_sext_i32_i16 s4, s4
	s_sext_i32_i8 s8, s8
	s_lshr_b32 s5, s3, 8
	v_or_b32_e32 v1, v8, v9
	v_and_or_b32 v3, v3, s7, v2
	v_lshrrev_b32_e32 v0, 7, v11
	s_movk_i32 s7, 0xf0
	s_lshr_b32 s4, s4, 3
	s_add_i32 s44, s9, s8
	v_and_b32_e32 v240, 7, v164
	v_bfe_u32 v241, v164, 4, 3
	v_xor_b32_e32 v240, v240, v241
	v_lshlrev_b32_e32 v240, 4, v240
	v_lshrrev_b32_e32 v241, 3, v164
	v_lshl_or_b32 v242, v241, 11, v240
	v_add_u32_e32 v243, 0x20000, v242
	v_bfe_u32 v244, v164, 5, 2
	v_lshlrev_b32_e32 v244, 3, v244
	v_bfe_u32 v245, v164, 7, 1
	v_lshl_or_b32 v244, v245, 2, v244
	v_bfe_u32 v245, v164, 3, 2
	v_or_b32_e32 v244, v244, v245
	v_bfe_u32 v245, v164, 8, 1
	v_lshl_or_b32 v247, v245, 5, v244
	v_lshl_or_b32 v244, v247, 11, v240
	v_add_u32_e32 v245, 0x20000, v244
	v_and_b32_e32 v246, 15, v164
	v_bfe_u32 v247, v164, 4, 2
	v_bfe_u32 v248, v164, 1, 3
	v_xor_b32_e32 v247, v247, v248
	v_lshlrev_b32_e32 v247, 4, v247
	v_lshl_or_b32 v246, v246, 7, v247
	v_mov_b32_e32 v134, v244
	v_and_or_b32 v3, v0, s7, v10
	s_movk_i32 s7, 0xe0
	s_lshr_b32 s18, s3, 6
	s_ashr_i32 s45, s44, 31
	s_bfe_i64 s[8:9], s[4:5], 0x100000
	v_and_or_b32 v0, v0, s7, v2
	s_lshl_b32 s7, s18, 10
	s_lshl_b64 s[14:15], s[44:45], 19
	s_lshl_b64 s[8:9], s[8:9], 19
	s_add_u32 s48, s64, s8
	s_addc_u32 s49, s65, s9
	s_add_i32 s8, s7, 0
	s_add_i32 m0, s8, 0x10000
	v_mov_b32_e32 v138, v245
	global_load_lds_dwordx4 v134, s[48:49]
	s_add_i32 m0, s8, 0x12000
	s_add_u32 s16, s48, 0x40000
	global_load_lds_dwordx4 v138, s[48:49]
	s_addc_u32 s17, s49, 0
	s_add_i32 m0, s8, 0x14000
	v_mov_b32_e32 v132, v242
	global_load_lds_dwordx4 v134, s[16:17]
	s_add_i32 m0, s8, 0x16000
	s_add_u32 s46, s56, s14
	s_addc_u32 s47, s57, s15
	s_add_i32 s9, s8, 0x2000
	global_load_lds_dwordx4 v138, s[16:17]
	s_mov_b32 m0, s8
	s_add_u32 s14, s46, 0x40000
	v_mov_b32_e32 v136, v243
	global_load_lds_dwordx4 v132, s[46:47]
	s_mov_b32 m0, s9
	s_addc_u32 s15, s47, 0
	s_add_i32 s34, s8, 0x4000
	global_load_lds_dwordx4 v136, s[46:47]
	s_mov_b32 m0, s34
	s_add_i32 s35, s8, 0x6000
	global_load_lds_dwordx4 v132, s[14:15]
	s_mov_b32 m0, s35
	v_mov_b32_e32 v135, 0
	global_load_lds_dwordx4 v136, s[14:15]
	v_mov_b32_e32 v139, v135
	v_mov_b32_e32 v133, v135
	v_mov_b32_e32 v137, v135
	s_cmp_eq_u32 s5, 1
	s_mov_b32 s52, 0
	v_lshl_add_u64 v[6:7], s[48:49], 0, v[134:135]
	v_lshl_add_u64 v[2:3], s[48:49], 0, v[138:139]
	s_mov_b64 s[14:15], 0x40000
	v_lshl_add_u64 v[0:1], s[46:47], 0, v[132:133]
	s_cselect_b64 s[16:17], -1, 0
	s_cmp_lg_u32 s5, 1
	v_lshl_add_u64 v[4:5], s[46:47], 0, v[136:137]
	s_cbranch_scc1 .LBB0_670
	s_barrier
.LBB0_670:
	s_lshl_b32 s18, s18, 5
	s_and_b32 s23, s18, 0x60
	s_mov_b64 s[18:19], 0x80
	s_add_i32 m0, s8, 0x18000
	v_lshl_add_u64 v[6:7], v[6:7], 0, s[18:19]
	s_lshl_b32 s22, s5, 13
	s_lshl_b32 s24, s23, 7
	s_waitcnt vmcnt(2)
	s_barrier
	global_load_lds_dwordx4 v[6:7], off
	v_lshl_add_u64 v[2:3], v[2:3], 0, s[18:19]
	s_add_i32 m0, s8, 0x1a000
	s_add_i32 s53, s8, 0x8000
	s_add_i32 s54, s8, 0xa000
	global_load_lds_dwordx4 v[2:3], off
	v_lshl_add_u64 v[0:1], v[0:1], 0, s[18:19]
	s_mov_b32 m0, s53
	s_add_u32 s20, s48, 0x40080
	global_load_lds_dwordx4 v[0:1], off
	v_lshl_add_u64 v[0:1], v[4:5], 0, s[18:19]
	s_mov_b32 m0, s54
	s_addc_u32 s21, s49, 0
	global_load_lds_dwordx4 v[0:1], off
	s_add_i32 m0, s8, 0x1c000
	v_lshl_add_u64 v[0:1], s[20:21], 0, v[134:135]
	global_load_lds_dwordx4 v[0:1], off
	v_lshl_add_u64 v[0:1], s[20:21], 0, v[138:139]
	s_add_i32 m0, s8, 0x1e000
	v_bfe_u32 v161, v164, 4, 2
	global_load_lds_dwordx4 v[0:1], off
	v_and_b32_e32 v160, 15, v164
	v_lshlrev_b32_e32 v163, 4, v161
	v_lshlrev_b32_e32 v1, 2, v164
	v_lshl_or_b32 v0, v160, 6, v163
	v_and_b32_e32 v1, 32, v1
	s_sext_i32_i8 s45, s4
	v_or_b32_e32 v2, s22, v246
	v_lshlrev_b32_e32 v0, 6, v164
	s_movk_i32 s4, 0x3c0
	v_and_or_b32 v0, v0, s4, v163
	v_or_b32_e32 v166, s24, v246
	v_lshlrev_b32_e32 v0, 6, v161
	v_mov_b32_e32 v1, v135
	v_lshl_add_u64 v[140:141], s[62:63], 0, v[0:1]
	v_lshlrev_b32_e32 v0, 8, v164
	v_and_b32_e32 v0, 0x38000, v0
	v_lshlrev_b32_e32 v1, 11, v10
	v_or3_b32 v0, v8, v0, v1
	v_mov_b32_e32 v142, v242
	v_lshlrev_b32_e32 v0, 4, v11
	v_and_b32_e32 v0, 0x78000, v0
	s_waitcnt vmcnt(6)
	s_cmpk_lt_u32 s3, 0x100
	v_or3_b32 v0, v8, v0, v1
	s_cselect_b64 s[20:21], -1, 0
	v_mov_b32_e32 v144, v243
	s_add_i32 s58, 0, 0x10000
	s_add_i32 s59, 0, 0x14000
	v_mbcnt_lo_u32_b32 v0, -1, 0
	v_lshl_or_b32 v162, s5, 6, v160
	s_ashr_i32 s55, s33, 31
	v_lshl_or_b32 v167, v161, 3, s23
	v_mov_b32_e32 v143, v135
	v_mov_b32_e32 v145, v135
	v_mov_b64_e32 v[146:147], 0x200
	v_mov_b64_e32 v[148:149], 0x1ff
	v_add_u32_e32 v168, s58, v166
	v_xor_b32_e32 v249, 64, v168
	v_add_u32_e32 v169, s59, v166
	v_xor_b32_e32 v250, 64, v169
	v_add_u32_e32 v170, 0, v2
	v_xor_b32_e32 v251, 64, v170
	v_mbcnt_hi_u32_b32 v171, -1, v0
	s_mov_b32 s68, 0x40000
	s_mov_b64 s[22:23], 0x48000
	s_mov_b32 s69, 0x48000
	s_mov_b64 s[24:25], 0x50000
	s_mov_b32 s70, 0x50000
	s_mov_b64 s[26:27], 0x58000
	s_mov_b32 s71, 0x58000
	s_barrier
	s_branch .LBB0_673

; #define PG8_STAGE(bufoff, gbase, voff) do { _Pragma("unroll") for (int _i = 0; _i < 2; ++_i) \
;         __builtin_amdgcn_global_load_lds((const unsigned*)((const char*)(gbase) + (voff)[_i]), (PG8_LAS unsigned*)(lds + (bufoff) + ldsw + _i * 8192), 16, 0, 0); } while (0)
; #define PG8_LDA(dst, b, h) do { _Pragma("unroll") for (int m = 0; m < 4; ++m) _Pragma("unroll") for (int k = 0; k < 2; ++k) dst[m][k] = *(const PG8_LAS bf16x8*)(lds + PG8_SA(b, h) + aoff + m * 2048 + k * 1024); } while (0)
; #define PG8_LDB(dst, b, h) do { _Pragma("unroll") for (int n = 0; n < 2; ++n) _Pragma("unroll") for (int k = 0; k < 2; ++k) dst[n][k] = *(const PG8_LAS bf16x8*)(lds + PG8_SB(b, h) + boff + n * 2048 + k * 1024); } while (0)
; #define PG8_MMA(ai, bj, At, Bt) do { __builtin_amdgcn_s_setprio(1); _Pragma("unroll") for (int m = 0; m < 4; ++m) _Pragma("unroll") for (int n = 0; n < 2; ++n) _Pragma("unroll") for (int k = 0; k < 2; ++k) \
;         acc[ai][bj][m][n] = __builtin_amdgcn_mfma_f32_16x16x32_bf16(Bt[n][k], At[m][k], acc[ai][bj][m][n], 0, 0, 0); __builtin_amdgcn_s_setprio(0); } while (0)
; #define PG8_WAIT_V(n) asm volatile("s_waitcnt vmcnt(" #n ")" ::: "memory")
; #define PG8_WAIT_L(n) asm volatile("s_waitcnt lgkmcnt(" #n ")" ::: "memory")
; #define PG8_BAR __builtin_amdgcn_s_barrier()
; #define PG8_SCHED __builtin_amdgcn_sched_barrier(0)
; template <class Epi, class Sched, bool ALIGN_EPI = false, bool SP2 = false>
; __device__ __forceinline__ void gemm_phase(PG8_LAS unsigned char* lds, const Gemm g, const Sched& S, const Epi& E) {
;     ...
;             PG8_LDB(B0, 0, 0); PG8_LDB(B1, 0, 1); PG8_SCHED; PG8_LDA(At, 0, 0); PG8_STAGE(PG8_SA(1, 1), a1 + hstep, voffA);
;             PG8_WAIT_V(8); PG8_WAIT_L(0); PG8_BAR; PG8_MMA(0, 0, At, B0); PG8_MMA(0, 1, At, B1); PG8_BAR; PG8_SCHED;
;             PG8_LDA(At, 0, 1); PG8_STAGE(PG8_SB(0, 0), b2, voffB); PG8_STAGE(PG8_SB(0, 1), b2 + hstep, voffB); PG8_STAGE(PG8_SA(0, 0), a2, voffA);
;             PG8_WAIT_V(8); PG8_WAIT_L(0); PG8_BAR; PG8_MMA(1, 0, At, B0); PG8_MMA(1, 1, At, B1); PG8_BAR; PG8_SCHED;
.LBB0_680:
	ds_read_b128 v[128:131], v168
	ds_read_b128 v[150:153], v249
	ds_read_b128 v[154:157], v168 offset:2048
	ds_read_b128 v[172:175], v249 offset:2048
	ds_read_b128 v[176:179], v169
	ds_read_b128 v[180:183], v250
	ds_read_b128 v[184:187], v169 offset:2048
	ds_read_b128 v[188:191], v250 offset:2048
	s_add_u32 s31, s46, 0xfffc0080
	s_addc_u32 s48, s47, -1
	s_cmp_eq_u32 s30, 12
	s_cselect_b32 s51, s37, s48
	s_cselect_b32 s50, s72, s31
	s_cselect_b32 s49, s39, s3
	s_cselect_b32 s48, s73, s74
	s_add_i32 m0, s8, 0xc000
	ds_read_b128 v[192:195], v170
	ds_read_b128 v[196:199], v251
	ds_read_b128 v[200:203], v170 offset:2048
	ds_read_b128 v[204:207], v251 offset:2048
	ds_read_b128 v[208:211], v170 offset:4096
	ds_read_b128 v[212:215], v251 offset:4096
	ds_read_b128 v[216:219], v170 offset:6144
	ds_read_b128 v[220:223], v251 offset:6144
	global_load_lds_dwordx4 v142, s[46:47]
	s_add_i32 m0, s8, 0xe000
	s_nop 0
	global_load_lds_dwordx4 v144, s[46:47]
	s_waitcnt vmcnt(8)
	s_waitcnt lgkmcnt(0)
	s_barrier
	s_setprio 1
	s_waitcnt lgkmcnt(0)
	v_mfma_f32_16x16x32_bf16 v[124:127], v[128:131], v[192:195], v[124:127]
	v_mfma_f32_16x16x32_bf16 v[120:123], v[154:157], v[192:195], v[120:123]
	v_mfma_f32_16x16x32_bf16 v[108:111], v[128:131], v[200:203], v[108:111]
	v_mfma_f32_16x16x32_bf16 v[104:107], v[154:157], v[200:203], v[104:107]
	v_mfma_f32_16x16x32_bf16 v[92:95], v[128:131], v[208:211], v[92:95]
	v_mfma_f32_16x16x32_bf16 v[88:91], v[154:157], v[208:211], v[88:91]
	v_mfma_f32_16x16x32_bf16 v[76:79], v[128:131], v[216:219], v[76:79]
	v_mfma_f32_16x16x32_bf16 v[72:75], v[154:157], v[216:219], v[72:75]
	v_mfma_f32_16x16x32_bf16 v[124:127], v[150:153], v[196:199], v[124:127]
	v_mfma_f32_16x16x32_bf16 v[120:123], v[172:175], v[196:199], v[120:123]
	v_mfma_f32_16x16x32_bf16 v[108:111], v[150:153], v[204:207], v[108:111]
	v_mfma_f32_16x16x32_bf16 v[104:107], v[172:175], v[204:207], v[104:107]
	v_mfma_f32_16x16x32_bf16 v[92:95], v[150:153], v[212:215], v[92:95]
	v_mfma_f32_16x16x32_bf16 v[88:91], v[172:175], v[212:215], v[88:91]
	v_mfma_f32_16x16x32_bf16 v[76:79], v[150:153], v[220:223], v[76:79]
	v_mfma_f32_16x16x32_bf16 v[72:75], v[172:175], v[220:223], v[72:75]
	s_setprio 0
	s_setprio 1
	v_mfma_f32_16x16x32_bf16 v[116:119], v[176:179], v[192:195], v[116:119]
	v_mfma_f32_16x16x32_bf16 v[112:115], v[184:187], v[192:195], v[112:115]
	v_mfma_f32_16x16x32_bf16 v[100:103], v[176:179], v[200:203], v[100:103]
	v_mfma_f32_16x16x32_bf16 v[96:99], v[184:187], v[200:203], v[96:99]
	v_mfma_f32_16x16x32_bf16 v[84:87], v[176:179], v[208:211], v[84:87]
	v_mfma_f32_16x16x32_bf16 v[80:83], v[184:187], v[208:211], v[80:83]
	v_mfma_f32_16x16x32_bf16 v[68:71], v[176:179], v[216:219], v[68:71]
	v_mfma_f32_16x16x32_bf16 v[64:67], v[184:187], v[216:219], v[64:67]
	v_mfma_f32_16x16x32_bf16 v[116:119], v[180:183], v[196:199], v[116:119]
	v_mfma_f32_16x16x32_bf16 v[112:115], v[188:191], v[196:199], v[112:115]
	v_mfma_f32_16x16x32_bf16 v[100:103], v[180:183], v[204:207], v[100:103]
	v_mfma_f32_16x16x32_bf16 v[96:99], v[188:191], v[204:207], v[96:99]
	v_mfma_f32_16x16x32_bf16 v[84:87], v[180:183], v[212:215], v[84:87]
	v_mfma_f32_16x16x32_bf16 v[80:83], v[188:191], v[212:215], v[80:83]
	v_mfma_f32_16x16x32_bf16 v[68:71], v[180:183], v[220:223], v[68:71]
	v_mfma_f32_16x16x32_bf16 v[64:67], v[188:191], v[220:223], v[64:67]
	s_setprio 0
	s_barrier
	s_add_i32 s31, s58, s7
	s_mov_b32 m0, s31
	ds_read_b128 v[192:195], v170 offset:16384
	ds_read_b128 v[196:199], v251 offset:16384
	ds_read_b128 v[200:203], v170 offset:18432
	ds_read_b128 v[204:207], v251 offset:18432
	ds_read_b128 v[208:211], v170 offset:20480
	ds_read_b128 v[212:215], v251 offset:20480
	ds_read_b128 v[216:219], v170 offset:22528
	ds_read_b128 v[220:223], v251 offset:22528
	global_load_lds_dwordx4 v134, s[48:49]
	s_add_i32 m0, s31, 0x2000
	s_add_u32 s76, s48, 0x40000
	s_addc_u32 s77, s49, 0
	s_add_i32 s31, s59, s7
	global_load_lds_dwordx4 v138, s[48:49]
	s_mov_b32 m0, s31
	s_nop 0
	global_load_lds_dwordx4 v134, s[76:77]
	s_add_i32 m0, s31, 0x2000
	s_nop 0
	global_load_lds_dwordx4 v138, s[76:77]
	s_mov_b32 m0, s8
	s_nop 0
	global_load_lds_dwordx4 v132, s[50:51]
	s_mov_b32 m0, s9
	s_nop 0
	global_load_lds_dwordx4 v136, s[50:51]
	s_waitcnt vmcnt(8)
	s_waitcnt lgkmcnt(0)
	s_barrier
	s_setprio 1
	s_waitcnt lgkmcnt(0)
	v_mfma_f32_16x16x32_bf16 v[60:63], v[128:131], v[192:195], v[60:63]
	v_mfma_f32_16x16x32_bf16 v[56:59], v[154:157], v[192:195], v[56:59]
	v_mfma_f32_16x16x32_bf16 v[44:47], v[128:131], v[200:203], v[44:47]
	v_mfma_f32_16x16x32_bf16 v[40:43], v[154:157], v[200:203], v[40:43]
	v_mfma_f32_16x16x32_bf16 v[28:31], v[128:131], v[208:211], v[28:31]
	v_mfma_f32_16x16x32_bf16 v[24:27], v[154:157], v[208:211], v[24:27]
	v_mfma_f32_16x16x32_bf16 v[16:19], v[128:131], v[216:219], v[16:19]
	v_mfma_f32_16x16x32_bf16 v[8:11], v[154:157], v[216:219], v[8:11]
	v_mfma_f32_16x16x32_bf16 v[60:63], v[150:153], v[196:199], v[60:63]
	v_mfma_f32_16x16x32_bf16 v[56:59], v[172:175], v[196:199], v[56:59]
	v_mfma_f32_16x16x32_bf16 v[44:47], v[150:153], v[204:207], v[44:47]
	v_mfma_f32_16x16x32_bf16 v[40:43], v[172:175], v[204:207], v[40:43]
	v_mfma_f32_16x16x32_bf16 v[28:31], v[150:153], v[212:215], v[28:31]
	v_mfma_f32_16x16x32_bf16 v[24:27], v[172:175], v[212:215], v[24:27]
	v_mfma_f32_16x16x32_bf16 v[16:19], v[150:153], v[220:223], v[16:19]
	v_mfma_f32_16x16x32_bf16 v[8:11], v[172:175], v[220:223], v[8:11]
	s_setprio 0
	s_setprio 1
	v_mfma_f32_16x16x32_bf16 v[52:55], v[176:179], v[192:195], v[52:55]
	v_mfma_f32_16x16x32_bf16 v[48:51], v[184:187], v[192:195], v[48:51]
	v_mfma_f32_16x16x32_bf16 v[36:39], v[176:179], v[200:203], v[36:39]
	v_mfma_f32_16x16x32_bf16 v[32:35], v[184:187], v[200:203], v[32:35]
	v_mfma_f32_16x16x32_bf16 v[20:23], v[176:179], v[208:211], v[20:23]
	v_mfma_f32_16x16x32_bf16 v[12:15], v[184:187], v[208:211], v[12:15]
	v_mfma_f32_16x16x32_bf16 v[4:7], v[176:179], v[216:219], v[4:7]
	v_mfma_f32_16x16x32_bf16 v[0:3], v[184:187], v[216:219], v[0:3]
	v_mfma_f32_16x16x32_bf16 v[52:55], v[180:183], v[196:199], v[52:55]
	v_mfma_f32_16x16x32_bf16 v[48:51], v[188:191], v[196:199], v[48:51]
	v_mfma_f32_16x16x32_bf16 v[36:39], v[180:183], v[204:207], v[36:39]
	v_mfma_f32_16x16x32_bf16 v[32:35], v[188:191], v[204:207], v[32:35]
	v_mfma_f32_16x16x32_bf16 v[20:23], v[180:183], v[212:215], v[20:23]
	v_mfma_f32_16x16x32_bf16 v[12:15], v[188:191], v[212:215], v[12:15]
	v_mfma_f32_16x16x32_bf16 v[4:7], v[180:183], v[220:223], v[4:7]
	v_mfma_f32_16x16x32_bf16 v[0:3], v[188:191], v[220:223], v[0:3]
	s_setprio 0
	s_barrier
; #define PG8_STAGE(bufoff, gbase, voff) do { _Pragma("unroll") for (int _i = 0; _i < 2; ++_i) \
;         __builtin_amdgcn_global_load_lds((const unsigned*)((const char*)(gbase) + (voff)[_i]), (PG8_LAS unsigned*)(lds + (bufoff) + ldsw + _i * 8192), 16, 0, 0); } while (0)
; #define PG8_LDA(dst, b, h) do { _Pragma("unroll") for (int m = 0; m < 4; ++m) _Pragma("unroll") for (int k = 0; k < 2; ++k) dst[m][k] = *(const PG8_LAS bf16x8*)(lds + PG8_SA(b, h) + aoff + m * 2048 + k * 1024); } while (0)
; #define PG8_LDB(dst, b, h) do { _Pragma("unroll") for (int n = 0; n < 2; ++n) _Pragma("unroll") for (int k = 0; k < 2; ++k) dst[n][k] = *(const PG8_LAS bf16x8*)(lds + PG8_SB(b, h) + boff + n * 2048 + k * 1024); } while (0)
; #define PG8_MMA(ai, bj, At, Bt) do { __builtin_amdgcn_s_setprio(1); _Pragma("unroll") for (int m = 0; m < 4; ++m) _Pragma("unroll") for (int n = 0; n < 2; ++n) _Pragma("unroll") for (int k = 0; k < 2; ++k) \
;         acc[ai][bj][m][n] = __builtin_amdgcn_mfma_f32_16x16x32_bf16(Bt[n][k], At[m][k], acc[ai][bj][m][n], 0, 0, 0); __builtin_amdgcn_s_setprio(0); } while (0)
; #define PG8_WAIT_V(n) asm volatile("s_waitcnt vmcnt(" #n ")" ::: "memory")
; #define PG8_WAIT_L(n) asm volatile("s_waitcnt lgkmcnt(" #n ")" ::: "memory")
; template <class Epi, class Sched, bool ALIGN_EPI = false, bool SP2 = false>
; __device__ __forceinline__ void gemm_phase(PG8_LAS unsigned char* lds, const Gemm g, const Sched& S, const Epi& E) {
;     ...
;         for (int t = 0; t < nt; t += 2) {
;             const bool last = (t == nt - 2);
;             const char* a1 = cA + (size_t)(t + 1) * kstep;
;             const char* a2 = last ? nA : cA + (size_t)(t + 2) * kstep; const char* b2 = last ? nB : cB + (size_t)(t + 2) * kstep;
;             const char* a3 = a2 + kstep; const char* b3 = b2 + kstep;
;             if (last && has_next) S.a_ready(nxt);
;     ...
;             PG8_LDB(B0, 1, 0); PG8_LDB(B1, 1, 1); PG8_SCHED; PG8_LDA(At, 1, 0); PG8_STAGE(PG8_SA(0, 1), a2 + hstep, voffA);
;             PG8_WAIT_V(8); PG8_WAIT_L(0); PG8_BAR; PG8_MMA(0, 0, At, B0); PG8_MMA(0, 1, At, B1); PG8_BAR; PG8_SCHED;
;             PG8_LDA(At, 1, 1); PG8_STAGE(PG8_SB(1, 0), b3, voffB); PG8_STAGE(PG8_SB(1, 1), b3 + hstep, voffB); PG8_STAGE(PG8_SA(1, 0), a3, voffA);
;             PG8_WAIT_V(8); PG8_WAIT_L(0); PG8_BAR; PG8_MMA(1, 0, At, B0); PG8_MMA(1, 1, At, B1); PG8_BAR; PG8_SCHED;
	s_add_i32 s31, 0, 0x18000
	v_add_u32_e32 v165, s31, v166
	v_xor_b32_e32 v252, 64, v165
	s_add_i32 s75, 0, 0x1c000
	ds_read_b128 v[128:131], v165
	ds_read_b128 v[150:153], v252
	ds_read_b128 v[154:157], v165 offset:2048
	ds_read_b128 v[172:175], v252 offset:2048
	v_add_u32_e32 v165, s75, v166
	v_xor_b32_e32 v252, 64, v165
	ds_read_b128 v[176:179], v165
	ds_read_b128 v[180:183], v252
	ds_read_b128 v[184:187], v165 offset:2048
	ds_read_b128 v[188:191], v252 offset:2048
	s_add_u32 s50, s50, 0x40000
	s_addc_u32 s51, s51, 0
	s_mov_b32 m0, s34
	ds_read_b128 v[192:195], v170 offset:32768
	ds_read_b128 v[196:199], v251 offset:32768
	ds_read_b128 v[200:203], v170 offset:34816
	ds_read_b128 v[204:207], v251 offset:34816
	ds_read_b128 v[208:211], v170 offset:36864
	ds_read_b128 v[212:215], v251 offset:36864
	ds_read_b128 v[216:219], v170 offset:38912
	ds_read_b128 v[220:223], v251 offset:38912
	global_load_lds_dwordx4 v132, s[50:51]
	s_mov_b32 m0, s35
	s_nop 0
	global_load_lds_dwordx4 v136, s[50:51]
	s_add_u32 s100, s48, 0x80
	s_addc_u32 s101, s49, 0
	s_sub_u32 s98, s50, 0x3ff80
	s_subb_u32 s99, s51, 0
	s_waitcnt vmcnt(8)
	s_waitcnt lgkmcnt(0)
	s_barrier
	s_setprio 1
	s_waitcnt lgkmcnt(0)
	v_mfma_f32_16x16x32_bf16 v[124:127], v[128:131], v[192:195], v[124:127]
	v_mfma_f32_16x16x32_bf16 v[120:123], v[154:157], v[192:195], v[120:123]
	v_mfma_f32_16x16x32_bf16 v[108:111], v[128:131], v[200:203], v[108:111]
	v_mfma_f32_16x16x32_bf16 v[104:107], v[154:157], v[200:203], v[104:107]
	v_mfma_f32_16x16x32_bf16 v[92:95], v[128:131], v[208:211], v[92:95]
	v_mfma_f32_16x16x32_bf16 v[88:91], v[154:157], v[208:211], v[88:91]
	v_mfma_f32_16x16x32_bf16 v[76:79], v[128:131], v[216:219], v[76:79]
	v_mfma_f32_16x16x32_bf16 v[72:75], v[154:157], v[216:219], v[72:75]
	v_mfma_f32_16x16x32_bf16 v[124:127], v[150:153], v[196:199], v[124:127]
	v_mfma_f32_16x16x32_bf16 v[120:123], v[172:175], v[196:199], v[120:123]
	v_mfma_f32_16x16x32_bf16 v[108:111], v[150:153], v[204:207], v[108:111]
	v_mfma_f32_16x16x32_bf16 v[104:107], v[172:175], v[204:207], v[104:107]
	v_mfma_f32_16x16x32_bf16 v[92:95], v[150:153], v[212:215], v[92:95]
	v_mfma_f32_16x16x32_bf16 v[88:91], v[172:175], v[212:215], v[88:91]
	v_mfma_f32_16x16x32_bf16 v[76:79], v[150:153], v[220:223], v[76:79]
	v_mfma_f32_16x16x32_bf16 v[72:75], v[172:175], v[220:223], v[72:75]
	s_setprio 0
	s_setprio 1
	v_mfma_f32_16x16x32_bf16 v[116:119], v[176:179], v[192:195], v[116:119]
	v_mfma_f32_16x16x32_bf16 v[112:115], v[184:187], v[192:195], v[112:115]
	v_mfma_f32_16x16x32_bf16 v[100:103], v[176:179], v[200:203], v[100:103]
	v_mfma_f32_16x16x32_bf16 v[96:99], v[184:187], v[200:203], v[96:99]
	v_mfma_f32_16x16x32_bf16 v[84:87], v[176:179], v[208:211], v[84:87]
	v_mfma_f32_16x16x32_bf16 v[80:83], v[184:187], v[208:211], v[80:83]
	v_mfma_f32_16x16x32_bf16 v[68:71], v[176:179], v[216:219], v[68:71]
	v_mfma_f32_16x16x32_bf16 v[64:67], v[184:187], v[216:219], v[64:67]
	v_mfma_f32_16x16x32_bf16 v[116:119], v[180:183], v[196:199], v[116:119]
	v_mfma_f32_16x16x32_bf16 v[112:115], v[188:191], v[196:199], v[112:115]
	v_mfma_f32_16x16x32_bf16 v[100:103], v[180:183], v[204:207], v[100:103]
	v_mfma_f32_16x16x32_bf16 v[96:99], v[188:191], v[204:207], v[96:99]
	v_mfma_f32_16x16x32_bf16 v[84:87], v[180:183], v[212:215], v[84:87]
	v_mfma_f32_16x16x32_bf16 v[80:83], v[188:191], v[212:215], v[80:83]
	v_mfma_f32_16x16x32_bf16 v[68:71], v[180:183], v[220:223], v[68:71]
	v_mfma_f32_16x16x32_bf16 v[64:67], v[188:191], v[220:223], v[64:67]
	s_setprio 0
	s_barrier
	s_add_i32 s31, s31, s7
	s_mov_b32 m0, s31
	ds_read_b128 v[192:195], v170 offset:49152
	ds_read_b128 v[196:199], v251 offset:49152
	ds_read_b128 v[200:203], v170 offset:51200
	ds_read_b128 v[204:207], v251 offset:51200
	ds_read_b128 v[208:211], v170 offset:53248
	ds_read_b128 v[212:215], v251 offset:53248
	ds_read_b128 v[216:219], v170 offset:55296
	ds_read_b128 v[220:223], v251 offset:55296
	global_load_lds_dwordx4 v134, s[100:101]
	s_add_i32 m0, s31, 0x2000
	s_add_u32 s48, s48, 0x40080
	s_addc_u32 s49, s49, 0
	s_add_i32 s31, s75, s7
	global_load_lds_dwordx4 v138, s[100:101]
	s_mov_b32 m0, s31
	s_nop 0
	global_load_lds_dwordx4 v134, s[48:49]
	s_add_i32 m0, s31, 0x2000
	s_nop 0
	global_load_lds_dwordx4 v138, s[48:49]
	s_mov_b32 m0, s53
	s_nop 0
	global_load_lds_dwordx4 v132, s[98:99]
	s_mov_b32 m0, s54
	s_nop 0
	global_load_lds_dwordx4 v136, s[98:99]
	s_waitcnt vmcnt(8)
	s_waitcnt lgkmcnt(0)
	s_barrier
	s_setprio 1
	s_waitcnt lgkmcnt(0)
	v_mfma_f32_16x16x32_bf16 v[60:63], v[128:131], v[192:195], v[60:63]
	v_mfma_f32_16x16x32_bf16 v[56:59], v[154:157], v[192:195], v[56:59]
	v_mfma_f32_16x16x32_bf16 v[44:47], v[128:131], v[200:203], v[44:47]
	v_mfma_f32_16x16x32_bf16 v[40:43], v[154:157], v[200:203], v[40:43]
	v_mfma_f32_16x16x32_bf16 v[28:31], v[128:131], v[208:211], v[28:31]
	v_mfma_f32_16x16x32_bf16 v[24:27], v[154:157], v[208:211], v[24:27]
	v_mfma_f32_16x16x32_bf16 v[16:19], v[128:131], v[216:219], v[16:19]
	v_mfma_f32_16x16x32_bf16 v[8:11], v[154:157], v[216:219], v[8:11]
	v_mfma_f32_16x16x32_bf16 v[60:63], v[150:153], v[196:199], v[60:63]
	v_mfma_f32_16x16x32_bf16 v[56:59], v[172:175], v[196:199], v[56:59]
	v_mfma_f32_16x16x32_bf16 v[44:47], v[150:153], v[204:207], v[44:47]
	v_mfma_f32_16x16x32_bf16 v[40:43], v[172:175], v[204:207], v[40:43]
	v_mfma_f32_16x16x32_bf16 v[28:31], v[150:153], v[212:215], v[28:31]
	v_mfma_f32_16x16x32_bf16 v[24:27], v[172:175], v[212:215], v[24:27]
	v_mfma_f32_16x16x32_bf16 v[16:19], v[150:153], v[220:223], v[16:19]
	v_mfma_f32_16x16x32_bf16 v[8:11], v[172:175], v[220:223], v[8:11]
	s_setprio 0
	s_setprio 1
	v_mfma_f32_16x16x32_bf16 v[52:55], v[176:179], v[192:195], v[52:55]
	v_mfma_f32_16x16x32_bf16 v[48:51], v[184:187], v[192:195], v[48:51]
	v_mfma_f32_16x16x32_bf16 v[36:39], v[176:179], v[200:203], v[36:39]
	v_mfma_f32_16x16x32_bf16 v[32:35], v[184:187], v[200:203], v[32:35]
	v_mfma_f32_16x16x32_bf16 v[20:23], v[176:179], v[208:211], v[20:23]
	v_mfma_f32_16x16x32_bf16 v[12:15], v[184:187], v[208:211], v[12:15]
	v_mfma_f32_16x16x32_bf16 v[4:7], v[176:179], v[216:219], v[4:7]
	v_mfma_f32_16x16x32_bf16 v[0:3], v[184:187], v[216:219], v[0:3]
	v_mfma_f32_16x16x32_bf16 v[52:55], v[180:183], v[196:199], v[52:55]
	v_mfma_f32_16x16x32_bf16 v[48:51], v[188:191], v[196:199], v[48:51]
	v_mfma_f32_16x16x32_bf16 v[36:39], v[180:183], v[204:207], v[36:39]
	v_mfma_f32_16x16x32_bf16 v[32:35], v[188:191], v[204:207], v[32:35]
	v_mfma_f32_16x16x32_bf16 v[20:23], v[180:183], v[212:215], v[20:23]
	v_mfma_f32_16x16x32_bf16 v[12:15], v[188:191], v[212:215], v[12:15]
	v_mfma_f32_16x16x32_bf16 v[4:7], v[180:183], v[220:223], v[4:7]
	v_mfma_f32_16x16x32_bf16 v[0:3], v[188:191], v[220:223], v[0:3]
	s_setprio 0
	s_barrier
	s_add_i32 s30, s30, 2
	s_add_u32 s46, s46, 0x100
	s_addc_u32 s47, s47, 0
	s_add_u32 s74, s74, 0x100
	s_addc_u32 s3, s3, 0
	s_cmp_gt_u32 s30, 13
	s_cbranch_scc0 .LBB0_680
	s_and_b64 vcc, exec, s[20:21]
	s_cbranch_vccz .LBB0_683
	s_barrier

;     __host__ __device__ bool next(int i, Unit& u) const { if (!so.next(i >> 1, u)) return false; u.seg = i & 1; return true; }
; #define PG8_WAIT_V(n) asm volatile("s_waitcnt vmcnt(" #n ")" ::: "memory")
; template <class Epi, class Sched, bool ALIGN_EPI = false, bool SP2 = false>
; __device__ __forceinline__ void gemm_phase(PG8_LAS unsigned char* lds, const Gemm g, const Sched& S, const Epi& E) {
;     ...
;     for (int i = 0; i < 2; ++i) { int R, C; stage_rc(tid * 16 + i * 8192, R, C); const int Rb = Epi::PERM ? ((R & ~31) + perm32(R & 31)) : R;
;         voffA[i] = (unsigned)(R * K + C) * 2u; voffB[i] = (unsigned)(Rb * K + C) * 2u; }
;     const size_t kstep = (size_t)(BK * 2);
;     const size_t hstep = (size_t)HALF * K * 2;
;     const size_t tstep = 2 * hstep;
;     const unsigned ldsw = (unsigned)wid * 1024u;
;     const int aoff = lds_byte(wr * 64 + fr, fq * 8), boff = lds_byte(wc * 32 + fr, fq * 8);
;     ...
;     Unit cur, nxt; int ui = 0;
;     if (!S.next(0, cur)) return;
;     f32x4 acc[2][2][4][2];
; #pragma unroll
;     for (int a = 0; a < 2; ++a)
; #pragma unroll
;         for (int b = 0; b < 2; ++b)
; #pragma unroll
;             for (int m = 0; m < 4; ++m)
; #pragma unroll
;                 for (int n = 0; n < 2; ++n) acc[a][b][m][n] = (f32x4){0.f, 0.f, 0.f, 0.f};
;     bf16x8 At[4][2], B0[2][2], B1[2][2];
;     const char* cA = (const char*)(cur.seg ? g.A1 : g.A0) + (size_t)cur.pm * tstep; const char* cB = (const char*)(cur.seg ? g.B1 : g.B0) + (size_t)cur.pn * tstep;
;     S.a_ready(cur);
;     if constexpr (SP2) {
;         PG8_STAGE(PG8_SB(0, 0), cB, voffB); PG8_STAGE(PG8_SB(0, 1), cB + hstep, voffB); PG8_STAGE(PG8_SA(0, 0), cA, voffA); PG8_STAGE(PG8_SA(0, 1), cA + hstep, voffA);
;         if (wr == 1) PG8_BAR;
;         PG8_WAIT_V(2); PG8_BAR;
;         PG8_STAGE(PG8_SB(1, 0), cB + kstep, voffB); PG8_STAGE(PG8_SA(1, 0), cA + kstep, voffA); PG8_STAGE(PG8_SB(1, 1), cB + hstep + kstep, voffB);
;         PG8_WAIT_V(6); PG8_BAR;
;     } else {
;         PG8_STAGE(PG8_SB(0, 0), cB, voffB); PG8_STAGE(PG8_SA(0, 0), cA, voffA); PG8_STAGE(PG8_SB(0, 1), cB + hstep, voffB); PG8_STAGE(PG8_SA(0, 1), cA + hstep, voffA);
;         if (wr == 1) PG8_BAR;
;         PG8_WAIT_V(4); PG8_BAR;
;         PG8_STAGE(PG8_SB(1, 0), cB + kstep, voffB); PG8_STAGE(PG8_SA(1, 0), cA + kstep, voffA); PG8_STAGE(PG8_SB(1, 1), cB + hstep + kstep, voffB);
;         PG8_WAIT_V(6); PG8_BAR;
.LBB0_860:
	s_add_i32 s1, s7, s1
	s_sext_i32_i16 s7, s1
	s_bfe_u32 s7, s7, 0x5001a
	s_add_i32 s7, s1, s7
	s_sext_i32_i16 s8, s7
	s_and_b32 s7, s7, 0xffe0
	s_waitcnt lgkmcnt(0)
	v_lshrrev_b32_e32 v3, 1, v164
	s_sub_i32 s7, s1, s7
	v_and_b32_e32 v10, 24, v3
	v_lshrrev_b32_e32 v3, 5, v164
	s_bfe_i32 s1, s7, 0x80000
	v_and_b32_e32 v3, 4, v3
	v_bfe_u32 v4, v164, 2, 2
	s_bfe_u32 s1, s1, 0x3000c
	v_lshlrev_b32_e32 v0, 4, v164
	v_and_b32_e32 v1, 32, v164
	v_bfe_u32 v2, v164, 2, 4
	v_or3_b32 v3, v3, v4, v10
	v_lshrrev_b32_e32 v4, 3, v164
	s_movk_i32 s5, 0x70
	s_add_i32 s9, s7, s1
	v_bitop3_b32 v8, v0, v1, 48 bitop3:0x6c
	v_and_or_b32 v5, v4, s5, v2
	s_movk_i32 s5, 0x60
	v_add_u32_e32 v0, 0x2000, v0
	s_bfe_i32 s1, s9, 0x80000
	s_and_b32 s9, s9, 0xf8
	v_and_or_b32 v4, v4, s5, v3
	v_lshrrev_b32_e32 v0, 7, v0
	s_movk_i32 s5, 0xf0
	s_ashr_i32 s8, s8, 5
	s_sub_i32 s7, s7, s9
	v_and_or_b32 v2, v0, s5, v2
	s_movk_i32 s5, 0xe0
	s_lshl_b32 s8, s8, 3
	s_sext_i32_i16 s14, s1
	s_sext_i32_i8 s7, s7
	v_and_b32_e32 v9, 64, v164
	v_and_or_b32 v0, v0, s5, v3
	s_lshr_b32 s5, s4, 6
	s_add_i32 s51, s8, s7
	s_ashr_i32 s7, s14, 3
	s_lshr_b32 s0, s4, 8
	v_or_b32_e32 v1, v8, v9
	s_lshl_b32 s6, s5, 10
	s_lshr_b32 s1, s14, 3
	s_mul_hi_i32 s8, s7, 0x160000
	s_mul_i32 s7, s7, 0x160000
	v_lshrrev_b32_e32 v1, 1, v1
	v_mul_u32_u24_e32 v4, 0xb00, v4
	s_add_u32 s36, s94, s7
	v_or_b32_e32 v4, v4, v1
	s_addc_u32 s37, s95, s8
	s_add_i32 s7, s6, 0
	v_and_b32_e32 v240, 7, v164
	v_bfe_u32 v241, v164, 4, 3
	v_xor_b32_e32 v240, v240, v241
	v_lshlrev_b32_e32 v240, 4, v240
	v_lshrrev_b32_e32 v241, 3, v164
	v_mul_u32_u24_e32 v242, 0x1600, v241
	v_add_u32_e32 v242, v242, v240
	v_add_u32_e32 v243, 0x58000, v242
	v_bfe_u32 v244, v164, 5, 2
	v_lshlrev_b32_e32 v244, 3, v244
	v_bfe_u32 v245, v164, 7, 1
	v_lshl_or_b32 v244, v245, 2, v244
	v_bfe_u32 v245, v164, 3, 2
	v_or_b32_e32 v244, v244, v245
	v_bfe_u32 v245, v164, 8, 1
	v_lshl_or_b32 v247, v245, 5, v244
	v_mul_u32_u24_e32 v244, 0x1600, v247
	v_add_u32_e32 v244, v244, v240
	v_add_u32_e32 v245, 0x58000, v244
	v_and_b32_e32 v246, 15, v164
	v_bfe_u32 v247, v164, 4, 2
	v_bfe_u32 v248, v164, 1, 3
	v_xor_b32_e32 v247, v247, v248
	v_lshlrev_b32_e32 v247, 4, v247
	v_lshl_or_b32 v246, v246, 7, v247
	v_mov_b32_e32 v130, v244
	v_mul_u32_u24_e32 v0, 0xb00, v0
	s_add_i32 m0, s7, 0x10000
	v_or_b32_e32 v0, v0, v1
	global_load_lds_dwordx4 v130, s[36:37]
	s_add_i32 m0, s7, 0x12000
	v_mov_b32_e32 v134, v245
	s_add_u32 s8, s36, 0xb0000
	global_load_lds_dwordx4 v134, s[36:37]
	s_addc_u32 s9, s37, 0
	s_add_i32 m0, s7, 0x14000
	s_mul_i32 s16, s51, 0x160000
	global_load_lds_dwordx4 v130, s[8:9]
	s_add_i32 m0, s7, 0x16000
	v_mul_u32_u24_e32 v11, 0xb00, v5
	s_mul_hi_i32 s15, s51, 0x160000
	s_add_u32 s34, s12, s16
	v_or_b32_e32 v5, v1, v11
	v_mul_u32_u24_e32 v12, 0xb00, v2
	s_addc_u32 s35, s13, s15
	s_add_i32 s40, s7, 0x2000
	v_mov_b32_e32 v128, v242
	v_or_b32_e32 v2, v12, v1
	global_load_lds_dwordx4 v134, s[8:9]
	s_mov_b32 m0, s7
	s_add_u32 s8, s34, 0xb0000
	v_mov_b32_e32 v132, v243
	global_load_lds_dwordx4 v128, s[34:35]
	s_mov_b32 m0, s40
	s_addc_u32 s9, s35, 0
	s_add_i32 s41, s7, 0x4000
	global_load_lds_dwordx4 v132, s[34:35]
	s_mov_b32 m0, s41
	s_add_i32 s42, s7, 0x6000
	global_load_lds_dwordx4 v128, s[8:9]
	s_mov_b32 m0, s42
	v_mov_b32_e32 v131, 0
	global_load_lds_dwordx4 v132, s[8:9]
	v_mov_b32_e32 v135, v131
	v_mov_b32_e32 v129, v131
	v_mov_b32_e32 v133, v131
	s_cmp_eq_u32 s0, 1
	s_mov_b32 s43, 0
	v_lshl_add_u64 v[6:7], s[36:37], 0, v[130:131]
	v_lshl_add_u64 v[4:5], s[36:37], 0, v[134:135]
	v_lshl_add_u64 v[0:1], s[34:35], 0, v[128:129]
	s_cselect_b64 s[8:9], -1, 0
	s_cmp_lg_u32 s0, 1
	v_lshl_add_u64 v[2:3], s[34:35], 0, v[132:133]
	s_cbranch_scc1 .LBB0_862
	s_barrier
.LBB0_862:
	s_lshl_b32 s5, s5, 5
	s_mov_b64 s[14:15], 0x80
	s_and_b32 s5, s5, 0x60
	s_add_i32 m0, s7, 0x18000
	v_lshl_add_u64 v[6:7], v[6:7], 0, s[14:15]
	s_lshl_b32 s18, s0, 13
	s_lshl_b32 s19, s5, 7
	s_waitcnt vmcnt(2)
	s_barrier
	global_load_lds_dwordx4 v[6:7], off
	v_lshl_add_u64 v[4:5], v[4:5], 0, s[14:15]
	s_add_i32 m0, s7, 0x1a000
	s_add_i32 s44, s7, 0x8000
	s_add_i32 s45, s7, 0xa000
	global_load_lds_dwordx4 v[4:5], off
	v_lshl_add_u64 v[0:1], v[0:1], 0, s[14:15]
	s_mov_b32 m0, s44
	s_add_u32 s16, s36, 0xb0080
	global_load_lds_dwordx4 v[0:1], off
	v_lshl_add_u64 v[0:1], v[2:3], 0, s[14:15]
	s_mov_b32 m0, s45
	s_addc_u32 s17, s37, 0
	global_load_lds_dwordx4 v[0:1], off
	s_add_i32 m0, s7, 0x1c000
	v_lshl_add_u64 v[0:1], s[16:17], 0, v[130:131]
	global_load_lds_dwordx4 v[0:1], off
	v_lshl_add_u64 v[0:1], s[16:17], 0, v[134:135]
	s_add_i32 m0, s7, 0x1e000
	v_lshlrev_b32_e32 v2, 2, v164
	global_load_lds_dwordx4 v[0:1], off
	v_and_b32_e32 v0, 15, v164
	v_lshl_or_b32 v150, s0, 6, v0
	v_lshlrev_b32_e32 v1, 1, v10
	v_lshlrev_b32_e32 v3, 6, v164
	s_movk_i32 s0, 0x3c0
	v_lshl_or_b32 v0, v0, 6, v1
	v_and_b32_e32 v2, 32, v2
	v_and_or_b32 v1, v3, s0, v1
	v_or_b32_e32 v151, s19, v246
	s_waitcnt vmcnt(6)
	s_cmpk_lt_u32 s4, 0x100
	v_add_u16_e32 v1, v8, v9
	v_or_b32_e32 v0, s18, v246
	s_cselect_b64 s[16:17], -1, 0
	v_lshrrev_b16_e32 v1, 1, v1
	s_add_i32 s47, 0, 0x10000
	s_add_i32 s48, 0, 0x14000
	s_sext_i32_i8 s52, s1
	s_ashr_i32 s46, s33, 31
	v_or_b32_e32 v152, s5, v10
	v_mov_b32_e32 v136, v242
	v_mov_b32_e32 v137, v131
	v_mov_b32_e32 v138, v243
	v_mov_b32_e32 v139, v131
	v_mov_b64_e32 v[140:141], 0x200
	v_mov_b64_e32 v[142:143], 0x1ff
	v_add_u32_e32 v153, s47, v151
	v_xor_b32_e32 v249, 64, v153
	v_add_u32_e32 v154, s48, v151
	v_xor_b32_e32 v250, 64, v154
	v_add_u32_e32 v155, 0, v0
	v_xor_b32_e32 v251, 64, v155
	s_mov_b64 s[18:19], 0x20000
	s_mov_b64 s[20:21], 0x24000
	s_mov_b64 s[22:23], 0x28000
	s_mov_b64 s[24:25], 0x2c000
	s_barrier
	s_branch .LBB0_865

; #define PG8_STAGE(bufoff, gbase, voff) do { _Pragma("unroll") for (int _i = 0; _i < 2; ++_i) \
;         __builtin_amdgcn_global_load_lds((const unsigned*)((const char*)(gbase) + (voff)[_i]), (PG8_LAS unsigned*)(lds + (bufoff) + ldsw + _i * 8192), 16, 0, 0); } while (0)
; #define PG8_LDA(dst, b, h) do { _Pragma("unroll") for (int m = 0; m < 4; ++m) _Pragma("unroll") for (int k = 0; k < 2; ++k) dst[m][k] = *(const PG8_LAS bf16x8*)(lds + PG8_SA(b, h) + aoff + m * 2048 + k * 1024); } while (0)
; #define PG8_LDB(dst, b, h) do { _Pragma("unroll") for (int n = 0; n < 2; ++n) _Pragma("unroll") for (int k = 0; k < 2; ++k) dst[n][k] = *(const PG8_LAS bf16x8*)(lds + PG8_SB(b, h) + boff + n * 2048 + k * 1024); } while (0)
; #define PG8_MMA(ai, bj, At, Bt) do { __builtin_amdgcn_s_setprio(1); _Pragma("unroll") for (int m = 0; m < 4; ++m) _Pragma("unroll") for (int n = 0; n < 2; ++n) _Pragma("unroll") for (int k = 0; k < 2; ++k) \
;         acc[ai][bj][m][n] = __builtin_amdgcn_mfma_f32_16x16x32_bf16(Bt[n][k], At[m][k], acc[ai][bj][m][n], 0, 0, 0); __builtin_amdgcn_s_setprio(0); } while (0)
; #define PG8_WAIT_V(n) asm volatile("s_waitcnt vmcnt(" #n ")" ::: "memory")
; #define PG8_WAIT_L(n) asm volatile("s_waitcnt lgkmcnt(" #n ")" ::: "memory")
; #define PG8_BAR __builtin_amdgcn_s_barrier()
; #define PG8_SCHED __builtin_amdgcn_sched_barrier(0)
; template <class Epi, class Sched, bool ALIGN_EPI = false, bool SP2 = false>
; __device__ __forceinline__ void gemm_phase(PG8_LAS unsigned char* lds, const Gemm g, const Sched& S, const Epi& E) {
;     ...
;             PG8_LDB(B0, 0, 0); PG8_LDB(B1, 0, 1); PG8_SCHED; PG8_LDA(At, 0, 0); PG8_STAGE(PG8_SA(1, 1), a1 + hstep, voffA);
;             PG8_WAIT_V(8); PG8_WAIT_L(0); PG8_BAR; PG8_MMA(0, 0, At, B0); PG8_MMA(0, 1, At, B1); PG8_BAR; PG8_SCHED;
;             PG8_LDA(At, 0, 1); PG8_STAGE(PG8_SB(0, 0), b2, voffB); PG8_STAGE(PG8_SB(0, 1), b2 + hstep, voffB); PG8_STAGE(PG8_SA(0, 0), a2, voffA);
;             PG8_WAIT_V(8); PG8_WAIT_L(0); PG8_BAR; PG8_MMA(1, 0, At, B0); PG8_MMA(1, 1, At, B1); PG8_BAR; PG8_SCHED;
.LBB0_876:
	ds_read_b128 v[144:147], v153
	ds_read_b128 v[156:159], v249
	ds_read_b128 v[160:163], v153 offset:2048
	ds_read_b128 v[166:169], v249 offset:2048
	ds_read_b128 v[170:173], v154
	ds_read_b128 v[174:177], v250
	ds_read_b128 v[178:181], v154 offset:2048
	ds_read_b128 v[182:185], v250 offset:2048
	s_add_u32 s31, s34, 0xfff50080
	s_addc_u32 s36, s35, -1
	s_cmp_eq_u32 s30, 40
	s_cselect_b32 s39, s1, s36
	s_cselect_b32 s38, s0, s31
	s_cselect_b32 s37, s27, s54
	s_cselect_b32 s36, s26, s53
	s_add_i32 m0, s7, 0xc000
	ds_read_b128 v[186:189], v155
	ds_read_b128 v[190:193], v251
	ds_read_b128 v[194:197], v155 offset:2048
	ds_read_b128 v[198:201], v251 offset:2048
	ds_read_b128 v[202:205], v155 offset:4096
	ds_read_b128 v[206:209], v251 offset:4096
	ds_read_b128 v[210:213], v155 offset:6144
	ds_read_b128 v[214:217], v251 offset:6144
	global_load_lds_dwordx4 v136, s[34:35]
	s_add_i32 m0, s7, 0xe000
	s_nop 0
	global_load_lds_dwordx4 v138, s[34:35]
	s_waitcnt vmcnt(8)
	s_waitcnt lgkmcnt(0)
	s_barrier
	s_setprio 1
	s_waitcnt lgkmcnt(0)
	v_mfma_f32_16x16x32_bf16 v[124:127], v[144:147], v[186:189], v[124:127]
	v_mfma_f32_16x16x32_bf16 v[120:123], v[160:163], v[186:189], v[120:123]
	v_mfma_f32_16x16x32_bf16 v[112:115], v[144:147], v[194:197], v[112:115]
	v_mfma_f32_16x16x32_bf16 v[104:107], v[160:163], v[194:197], v[104:107]
	v_mfma_f32_16x16x32_bf16 v[96:99], v[144:147], v[202:205], v[96:99]
	v_mfma_f32_16x16x32_bf16 v[88:91], v[160:163], v[202:205], v[88:91]
	v_mfma_f32_16x16x32_bf16 v[80:83], v[144:147], v[210:213], v[80:83]
	v_mfma_f32_16x16x32_bf16 v[72:75], v[160:163], v[210:213], v[72:75]
	v_mfma_f32_16x16x32_bf16 v[124:127], v[156:159], v[190:193], v[124:127]
	v_mfma_f32_16x16x32_bf16 v[120:123], v[166:169], v[190:193], v[120:123]
	v_mfma_f32_16x16x32_bf16 v[112:115], v[156:159], v[198:201], v[112:115]
	v_mfma_f32_16x16x32_bf16 v[104:107], v[166:169], v[198:201], v[104:107]
	v_mfma_f32_16x16x32_bf16 v[96:99], v[156:159], v[206:209], v[96:99]
	v_mfma_f32_16x16x32_bf16 v[88:91], v[166:169], v[206:209], v[88:91]
	v_mfma_f32_16x16x32_bf16 v[80:83], v[156:159], v[214:217], v[80:83]
	v_mfma_f32_16x16x32_bf16 v[72:75], v[166:169], v[214:217], v[72:75]
	s_setprio 0
	s_setprio 1
	v_mfma_f32_16x16x32_bf16 v[116:119], v[170:173], v[186:189], v[116:119]
	v_mfma_f32_16x16x32_bf16 v[108:111], v[178:181], v[186:189], v[108:111]
	v_mfma_f32_16x16x32_bf16 v[100:103], v[170:173], v[194:197], v[100:103]
	v_mfma_f32_16x16x32_bf16 v[92:95], v[178:181], v[194:197], v[92:95]
	v_mfma_f32_16x16x32_bf16 v[84:87], v[170:173], v[202:205], v[84:87]
	v_mfma_f32_16x16x32_bf16 v[76:79], v[178:181], v[202:205], v[76:79]
	v_mfma_f32_16x16x32_bf16 v[68:71], v[170:173], v[210:213], v[68:71]
	v_mfma_f32_16x16x32_bf16 v[64:67], v[178:181], v[210:213], v[64:67]
	v_mfma_f32_16x16x32_bf16 v[116:119], v[174:177], v[190:193], v[116:119]
	v_mfma_f32_16x16x32_bf16 v[108:111], v[182:185], v[190:193], v[108:111]
	v_mfma_f32_16x16x32_bf16 v[100:103], v[174:177], v[198:201], v[100:103]
	v_mfma_f32_16x16x32_bf16 v[92:95], v[182:185], v[198:201], v[92:95]
	v_mfma_f32_16x16x32_bf16 v[84:87], v[174:177], v[206:209], v[84:87]
	v_mfma_f32_16x16x32_bf16 v[76:79], v[182:185], v[206:209], v[76:79]
	v_mfma_f32_16x16x32_bf16 v[68:71], v[174:177], v[214:217], v[68:71]
	v_mfma_f32_16x16x32_bf16 v[64:67], v[182:185], v[214:217], v[64:67]
	s_setprio 0
	s_barrier
	s_add_i32 s31, s47, s6
	s_mov_b32 m0, s31
	ds_read_b128 v[186:189], v155 offset:16384
	ds_read_b128 v[190:193], v251 offset:16384
	ds_read_b128 v[194:197], v155 offset:18432
	ds_read_b128 v[198:201], v251 offset:18432
	ds_read_b128 v[202:205], v155 offset:20480
	ds_read_b128 v[206:209], v251 offset:20480
	ds_read_b128 v[210:213], v155 offset:22528
	ds_read_b128 v[214:217], v251 offset:22528
	global_load_lds_dwordx4 v130, s[36:37]
	s_add_i32 m0, s31, 0x2000
	s_add_u32 s58, s36, 0xb0000
	s_addc_u32 s59, s37, 0
	s_add_i32 s31, s48, s6
	global_load_lds_dwordx4 v134, s[36:37]
	s_mov_b32 m0, s31
	s_nop 0
	global_load_lds_dwordx4 v130, s[58:59]
	s_add_i32 m0, s31, 0x2000
	s_nop 0
	global_load_lds_dwordx4 v134, s[58:59]
	s_mov_b32 m0, s7
	s_nop 0
	global_load_lds_dwordx4 v128, s[38:39]
	s_mov_b32 m0, s40
	s_nop 0
	global_load_lds_dwordx4 v132, s[38:39]
	s_waitcnt vmcnt(8)
	s_waitcnt lgkmcnt(0)
	s_barrier
	s_setprio 1
	s_waitcnt lgkmcnt(0)
	v_mfma_f32_16x16x32_bf16 v[60:63], v[144:147], v[186:189], v[60:63]
	v_mfma_f32_16x16x32_bf16 v[56:59], v[160:163], v[186:189], v[56:59]
	v_mfma_f32_16x16x32_bf16 v[48:51], v[144:147], v[194:197], v[48:51]
	v_mfma_f32_16x16x32_bf16 v[40:43], v[160:163], v[194:197], v[40:43]
	v_mfma_f32_16x16x32_bf16 v[32:35], v[144:147], v[202:205], v[32:35]
	v_mfma_f32_16x16x32_bf16 v[24:27], v[160:163], v[202:205], v[24:27]
	v_mfma_f32_16x16x32_bf16 v[16:19], v[144:147], v[210:213], v[16:19]
	v_mfma_f32_16x16x32_bf16 v[8:11], v[160:163], v[210:213], v[8:11]
	v_mfma_f32_16x16x32_bf16 v[60:63], v[156:159], v[190:193], v[60:63]
	v_mfma_f32_16x16x32_bf16 v[56:59], v[166:169], v[190:193], v[56:59]
	v_mfma_f32_16x16x32_bf16 v[48:51], v[156:159], v[198:201], v[48:51]
	v_mfma_f32_16x16x32_bf16 v[40:43], v[166:169], v[198:201], v[40:43]
	v_mfma_f32_16x16x32_bf16 v[32:35], v[156:159], v[206:209], v[32:35]
	v_mfma_f32_16x16x32_bf16 v[24:27], v[166:169], v[206:209], v[24:27]
	v_mfma_f32_16x16x32_bf16 v[16:19], v[156:159], v[214:217], v[16:19]
	v_mfma_f32_16x16x32_bf16 v[8:11], v[166:169], v[214:217], v[8:11]
	s_setprio 0
	s_setprio 1
	v_mfma_f32_16x16x32_bf16 v[52:55], v[170:173], v[186:189], v[52:55]
	v_mfma_f32_16x16x32_bf16 v[44:47], v[178:181], v[186:189], v[44:47]
	v_mfma_f32_16x16x32_bf16 v[36:39], v[170:173], v[194:197], v[36:39]
	v_mfma_f32_16x16x32_bf16 v[28:31], v[178:181], v[194:197], v[28:31]
	v_mfma_f32_16x16x32_bf16 v[20:23], v[170:173], v[202:205], v[20:23]
	v_mfma_f32_16x16x32_bf16 v[12:15], v[178:181], v[202:205], v[12:15]
	v_mfma_f32_16x16x32_bf16 v[4:7], v[170:173], v[210:213], v[4:7]
	v_mfma_f32_16x16x32_bf16 v[0:3], v[178:181], v[210:213], v[0:3]
	v_mfma_f32_16x16x32_bf16 v[52:55], v[174:177], v[190:193], v[52:55]
	v_mfma_f32_16x16x32_bf16 v[44:47], v[182:185], v[190:193], v[44:47]
	v_mfma_f32_16x16x32_bf16 v[36:39], v[174:177], v[198:201], v[36:39]
	v_mfma_f32_16x16x32_bf16 v[28:31], v[182:185], v[198:201], v[28:31]
	v_mfma_f32_16x16x32_bf16 v[20:23], v[174:177], v[206:209], v[20:23]
	v_mfma_f32_16x16x32_bf16 v[12:15], v[182:185], v[206:209], v[12:15]
	v_mfma_f32_16x16x32_bf16 v[4:7], v[174:177], v[214:217], v[4:7]
	v_mfma_f32_16x16x32_bf16 v[0:3], v[182:185], v[214:217], v[0:3]
	s_setprio 0
	s_barrier
; #define PG8_STAGE(bufoff, gbase, voff) do { _Pragma("unroll") for (int _i = 0; _i < 2; ++_i) \
;         __builtin_amdgcn_global_load_lds((const unsigned*)((const char*)(gbase) + (voff)[_i]), (PG8_LAS unsigned*)(lds + (bufoff) + ldsw + _i * 8192), 16, 0, 0); } while (0)
; #define PG8_LDA(dst, b, h) do { _Pragma("unroll") for (int m = 0; m < 4; ++m) _Pragma("unroll") for (int k = 0; k < 2; ++k) dst[m][k] = *(const PG8_LAS bf16x8*)(lds + PG8_SA(b, h) + aoff + m * 2048 + k * 1024); } while (0)
; #define PG8_LDB(dst, b, h) do { _Pragma("unroll") for (int n = 0; n < 2; ++n) _Pragma("unroll") for (int k = 0; k < 2; ++k) dst[n][k] = *(const PG8_LAS bf16x8*)(lds + PG8_SB(b, h) + boff + n * 2048 + k * 1024); } while (0)
; #define PG8_MMA(ai, bj, At, Bt) do { __builtin_amdgcn_s_setprio(1); _Pragma("unroll") for (int m = 0; m < 4; ++m) _Pragma("unroll") for (int n = 0; n < 2; ++n) _Pragma("unroll") for (int k = 0; k < 2; ++k) \
;         acc[ai][bj][m][n] = __builtin_amdgcn_mfma_f32_16x16x32_bf16(Bt[n][k], At[m][k], acc[ai][bj][m][n], 0, 0, 0); __builtin_amdgcn_s_setprio(0); } while (0)
; #define PG8_WAIT_V(n) asm volatile("s_waitcnt vmcnt(" #n ")" ::: "memory")
; #define PG8_WAIT_L(n) asm volatile("s_waitcnt lgkmcnt(" #n ")" ::: "memory")
; template <class Epi, class Sched, bool ALIGN_EPI = false, bool SP2 = false>
; __device__ __forceinline__ void gemm_phase(PG8_LAS unsigned char* lds, const Gemm g, const Sched& S, const Epi& E) {
;     ...
;         for (int t = 0; t < nt; t += 2) {
;             const bool last = (t == nt - 2);
;             const char* a1 = cA + (size_t)(t + 1) * kstep;
;             const char* a2 = last ? nA : cA + (size_t)(t + 2) * kstep; const char* b2 = last ? nB : cB + (size_t)(t + 2) * kstep;
;             const char* a3 = a2 + kstep; const char* b3 = b2 + kstep;
;             if (last && has_next) S.a_ready(nxt);
;     ...
;             PG8_LDB(B0, 1, 0); PG8_LDB(B1, 1, 1); PG8_SCHED; PG8_LDA(At, 1, 0); PG8_STAGE(PG8_SA(0, 1), a2 + hstep, voffA);
;             PG8_WAIT_V(8); PG8_WAIT_L(0); PG8_BAR; PG8_MMA(0, 0, At, B0); PG8_MMA(0, 1, At, B1); PG8_BAR; PG8_SCHED;
;             PG8_LDA(At, 1, 1); PG8_STAGE(PG8_SB(1, 0), b3, voffB); PG8_STAGE(PG8_SB(1, 1), b3 + hstep, voffB); PG8_STAGE(PG8_SA(1, 0), a3, voffA);
;             PG8_WAIT_V(8); PG8_WAIT_L(0); PG8_BAR; PG8_MMA(1, 0, At, B0); PG8_MMA(1, 1, At, B1); PG8_BAR; PG8_SCHED;
	s_add_i32 s31, 0, 0x18000
	v_add_u32_e32 v165, s31, v151
	v_xor_b32_e32 v252, 64, v165
	s_add_i32 s55, 0, 0x1c000
	ds_read_b128 v[144:147], v165
	ds_read_b128 v[156:159], v252
	ds_read_b128 v[160:163], v165 offset:2048
	ds_read_b128 v[166:169], v252 offset:2048
	v_add_u32_e32 v165, s55, v151
	v_xor_b32_e32 v252, 64, v165
	ds_read_b128 v[170:173], v165
	ds_read_b128 v[174:177], v252
	ds_read_b128 v[178:181], v165 offset:2048
	ds_read_b128 v[182:185], v252 offset:2048
	s_add_u32 s38, s38, 0xb0000
	s_addc_u32 s39, s39, 0
	s_mov_b32 m0, s41
	ds_read_b128 v[186:189], v155 offset:32768
	ds_read_b128 v[190:193], v251 offset:32768
	ds_read_b128 v[194:197], v155 offset:34816
	ds_read_b128 v[198:201], v251 offset:34816
	ds_read_b128 v[202:205], v155 offset:36864
	ds_read_b128 v[206:209], v251 offset:36864
	ds_read_b128 v[210:213], v155 offset:38912
	ds_read_b128 v[214:217], v251 offset:38912
	global_load_lds_dwordx4 v128, s[38:39]
	s_mov_b32 m0, s42
	s_nop 0
	global_load_lds_dwordx4 v132, s[38:39]
	s_add_u32 s100, s36, 0x80
	s_addc_u32 s101, s37, 0
	s_sub_u32 s98, s38, 0xaff80
	s_subb_u32 s99, s39, 0
	s_waitcnt vmcnt(8)
	s_waitcnt lgkmcnt(0)
	s_barrier
	s_setprio 1
	s_waitcnt lgkmcnt(0)
	v_mfma_f32_16x16x32_bf16 v[124:127], v[144:147], v[186:189], v[124:127]
	v_mfma_f32_16x16x32_bf16 v[120:123], v[160:163], v[186:189], v[120:123]
	v_mfma_f32_16x16x32_bf16 v[112:115], v[144:147], v[194:197], v[112:115]
	v_mfma_f32_16x16x32_bf16 v[104:107], v[160:163], v[194:197], v[104:107]
	v_mfma_f32_16x16x32_bf16 v[96:99], v[144:147], v[202:205], v[96:99]
	v_mfma_f32_16x16x32_bf16 v[88:91], v[160:163], v[202:205], v[88:91]
	v_mfma_f32_16x16x32_bf16 v[80:83], v[144:147], v[210:213], v[80:83]
	v_mfma_f32_16x16x32_bf16 v[72:75], v[160:163], v[210:213], v[72:75]
	v_mfma_f32_16x16x32_bf16 v[124:127], v[156:159], v[190:193], v[124:127]
	v_mfma_f32_16x16x32_bf16 v[120:123], v[166:169], v[190:193], v[120:123]
	v_mfma_f32_16x16x32_bf16 v[112:115], v[156:159], v[198:201], v[112:115]
	v_mfma_f32_16x16x32_bf16 v[104:107], v[166:169], v[198:201], v[104:107]
	v_mfma_f32_16x16x32_bf16 v[96:99], v[156:159], v[206:209], v[96:99]
	v_mfma_f32_16x16x32_bf16 v[88:91], v[166:169], v[206:209], v[88:91]
	v_mfma_f32_16x16x32_bf16 v[80:83], v[156:159], v[214:217], v[80:83]
	v_mfma_f32_16x16x32_bf16 v[72:75], v[166:169], v[214:217], v[72:75]
	s_setprio 0
	s_setprio 1
	v_mfma_f32_16x16x32_bf16 v[116:119], v[170:173], v[186:189], v[116:119]
	v_mfma_f32_16x16x32_bf16 v[108:111], v[178:181], v[186:189], v[108:111]
	v_mfma_f32_16x16x32_bf16 v[100:103], v[170:173], v[194:197], v[100:103]
	v_mfma_f32_16x16x32_bf16 v[92:95], v[178:181], v[194:197], v[92:95]
	v_mfma_f32_16x16x32_bf16 v[84:87], v[170:173], v[202:205], v[84:87]
	v_mfma_f32_16x16x32_bf16 v[76:79], v[178:181], v[202:205], v[76:79]
	v_mfma_f32_16x16x32_bf16 v[68:71], v[170:173], v[210:213], v[68:71]
	v_mfma_f32_16x16x32_bf16 v[64:67], v[178:181], v[210:213], v[64:67]
	v_mfma_f32_16x16x32_bf16 v[116:119], v[174:177], v[190:193], v[116:119]
	v_mfma_f32_16x16x32_bf16 v[108:111], v[182:185], v[190:193], v[108:111]
	v_mfma_f32_16x16x32_bf16 v[100:103], v[174:177], v[198:201], v[100:103]
	v_mfma_f32_16x16x32_bf16 v[92:95], v[182:185], v[198:201], v[92:95]
	v_mfma_f32_16x16x32_bf16 v[84:87], v[174:177], v[206:209], v[84:87]
	v_mfma_f32_16x16x32_bf16 v[76:79], v[182:185], v[206:209], v[76:79]
	v_mfma_f32_16x16x32_bf16 v[68:71], v[174:177], v[214:217], v[68:71]
	v_mfma_f32_16x16x32_bf16 v[64:67], v[182:185], v[214:217], v[64:67]
	s_setprio 0
	s_barrier
	s_add_i32 s31, s31, s6
	s_mov_b32 m0, s31
	ds_read_b128 v[186:189], v155 offset:49152
	ds_read_b128 v[190:193], v251 offset:49152
	ds_read_b128 v[194:197], v155 offset:51200
	ds_read_b128 v[198:201], v251 offset:51200
	ds_read_b128 v[202:205], v155 offset:53248
	ds_read_b128 v[206:209], v251 offset:53248
	ds_read_b128 v[210:213], v155 offset:55296
	ds_read_b128 v[214:217], v251 offset:55296
	global_load_lds_dwordx4 v130, s[100:101]
	s_add_i32 m0, s31, 0x2000
	s_add_u32 s36, s36, 0xb0080
	s_addc_u32 s37, s37, 0
	s_add_i32 s31, s55, s6
	global_load_lds_dwordx4 v134, s[100:101]
	s_mov_b32 m0, s31
	s_nop 0
	global_load_lds_dwordx4 v130, s[36:37]
	s_add_i32 m0, s31, 0x2000
	s_nop 0
	global_load_lds_dwordx4 v134, s[36:37]
	s_mov_b32 m0, s44
	s_nop 0
	global_load_lds_dwordx4 v128, s[98:99]
	s_mov_b32 m0, s45
	s_nop 0
	global_load_lds_dwordx4 v132, s[98:99]
	s_waitcnt vmcnt(8)
	s_waitcnt lgkmcnt(0)
	s_barrier
	s_setprio 1
	s_waitcnt lgkmcnt(0)
	v_mfma_f32_16x16x32_bf16 v[60:63], v[144:147], v[186:189], v[60:63]
	v_mfma_f32_16x16x32_bf16 v[56:59], v[160:163], v[186:189], v[56:59]
	v_mfma_f32_16x16x32_bf16 v[48:51], v[144:147], v[194:197], v[48:51]
	v_mfma_f32_16x16x32_bf16 v[40:43], v[160:163], v[194:197], v[40:43]
	v_mfma_f32_16x16x32_bf16 v[32:35], v[144:147], v[202:205], v[32:35]
	v_mfma_f32_16x16x32_bf16 v[24:27], v[160:163], v[202:205], v[24:27]
	v_mfma_f32_16x16x32_bf16 v[16:19], v[144:147], v[210:213], v[16:19]
	v_mfma_f32_16x16x32_bf16 v[8:11], v[160:163], v[210:213], v[8:11]
	v_mfma_f32_16x16x32_bf16 v[60:63], v[156:159], v[190:193], v[60:63]
	v_mfma_f32_16x16x32_bf16 v[56:59], v[166:169], v[190:193], v[56:59]
	v_mfma_f32_16x16x32_bf16 v[48:51], v[156:159], v[198:201], v[48:51]
	v_mfma_f32_16x16x32_bf16 v[40:43], v[166:169], v[198:201], v[40:43]
	v_mfma_f32_16x16x32_bf16 v[32:35], v[156:159], v[206:209], v[32:35]
	v_mfma_f32_16x16x32_bf16 v[24:27], v[166:169], v[206:209], v[24:27]
	v_mfma_f32_16x16x32_bf16 v[16:19], v[156:159], v[214:217], v[16:19]
	v_mfma_f32_16x16x32_bf16 v[8:11], v[166:169], v[214:217], v[8:11]
	s_setprio 0
	s_setprio 1
	v_mfma_f32_16x16x32_bf16 v[52:55], v[170:173], v[186:189], v[52:55]
	v_mfma_f32_16x16x32_bf16 v[44:47], v[178:181], v[186:189], v[44:47]
	v_mfma_f32_16x16x32_bf16 v[36:39], v[170:173], v[194:197], v[36:39]
	v_mfma_f32_16x16x32_bf16 v[28:31], v[178:181], v[194:197], v[28:31]
	v_mfma_f32_16x16x32_bf16 v[20:23], v[170:173], v[202:205], v[20:23]
	v_mfma_f32_16x16x32_bf16 v[12:15], v[178:181], v[202:205], v[12:15]
	v_mfma_f32_16x16x32_bf16 v[4:7], v[170:173], v[210:213], v[4:7]
	v_mfma_f32_16x16x32_bf16 v[0:3], v[178:181], v[210:213], v[0:3]
	v_mfma_f32_16x16x32_bf16 v[52:55], v[174:177], v[190:193], v[52:55]
	v_mfma_f32_16x16x32_bf16 v[44:47], v[182:185], v[190:193], v[44:47]
	v_mfma_f32_16x16x32_bf16 v[36:39], v[174:177], v[198:201], v[36:39]
	v_mfma_f32_16x16x32_bf16 v[28:31], v[182:185], v[198:201], v[28:31]
	v_mfma_f32_16x16x32_bf16 v[20:23], v[174:177], v[206:209], v[20:23]
	v_mfma_f32_16x16x32_bf16 v[12:15], v[182:185], v[206:209], v[12:15]
	v_mfma_f32_16x16x32_bf16 v[4:7], v[174:177], v[214:217], v[4:7]
	v_mfma_f32_16x16x32_bf16 v[0:3], v[182:185], v[214:217], v[0:3]
	s_setprio 0
	s_barrier
	s_add_i32 s30, s30, 2
	s_add_u32 s34, s34, 0x100
	s_addc_u32 s35, s35, 0
	s_add_u32 s53, s53, 0x100
	s_addc_u32 s54, s54, 0
	s_cmp_gt_u32 s30, 41
	s_cbranch_scc0 .LBB0_876
	s_and_b64 vcc, exec, s[16:17]
	s_cbranch_vccz .LBB0_879
	s_barrier
